# P2 decode attention streaming loop: real double buffering of K/V cache batches (next batch requested before waiting, counted waits +16), dummy batch on the last trip for path-independent counts
# speedup vs baseline: 1.0064x; 1.0064x over previous
; __device__ __forceinline__ void c_issue(CBuf& B, const float* kbase, const float* vbase, long rstride, int off) {
; #pragma unroll
;     for (int q = 0; q < 8; ++q) { B.k[q] = __builtin_nontemporal_load((const f32x4*)(kbase + (long)q * rstride + off)); B.v[q] = __builtin_nontemporal_load((const f32x4*)(vbase + (long)q * rstride + off)); }
; }
; __device__ __forceinline__ void c_desc(int b, int ws, long& idx, long& rstride, int& d0, int& dstep, int& tsel) {
;     if (b < 4) { idx = LB - 128 + 32 * ws + 8 * b; rstride = 512; d0 = 128 - 32 * ws - 8 * b; dstep = -1; tsel = -1; }
;     else { const int bb = b - 4, t = bb / 6, i = bb % 6, st = (i < 3) ? 4 : 16, j0 = 33 + 24 * ws + 8 * (i % 3); idx = LB + t - st * j0; rstride = -(long)st * 512; d0 = st * j0 - t; dstep = st; tsel = t; }
.LBB0_765:
	s_lshl_b64 s[6:7], s[10:11], 11
	s_nop 0
	v_lshl_add_u64 v[78:79], v[160:161], 0, s[6:7]
	s_lshl_b64 s[4:5], s[4:5], 2
	v_lshl_add_u64 v[80:81], v[162:163], 0, s[6:7]
	global_load_dwordx4 v[146:149], v[78:79], off nt
	global_load_dwordx4 v[118:121], v[80:81], off nt
	v_lshl_add_u64 v[78:79], v[78:79], 0, s[4:5]
	global_load_dwordx4 v[142:145], v[78:79], off nt
	v_lshl_add_u64 v[80:81], v[80:81], 0, s[4:5]
	v_lshl_add_u64 v[78:79], v[78:79], 0, s[4:5]
	global_load_dwordx4 v[122:125], v[80:81], off nt
	global_load_dwordx4 v[138:141], v[78:79], off nt
	v_lshl_add_u64 v[80:81], v[80:81], 0, s[4:5]
	v_lshl_add_u64 v[78:79], v[78:79], 0, s[4:5]
	global_load_dwordx4 v[114:117], v[80:81], off nt
	global_load_dwordx4 v[134:137], v[78:79], off nt
	v_lshl_add_u64 v[80:81], v[80:81], 0, s[4:5]
	v_lshl_add_u64 v[78:79], v[78:79], 0, s[4:5]
	global_load_dwordx4 v[110:113], v[80:81], off nt
	global_load_dwordx4 v[130:133], v[78:79], off nt
	v_lshl_add_u64 v[80:81], v[80:81], 0, s[4:5]
	v_lshl_add_u64 v[78:79], v[78:79], 0, s[4:5]
	global_load_dwordx4 v[106:109], v[80:81], off nt
	global_load_dwordx4 v[126:129], v[78:79], off nt
	v_lshl_add_u64 v[80:81], v[80:81], 0, s[4:5]
	v_lshl_add_u64 v[78:79], v[78:79], 0, s[4:5]
	global_load_dwordx4 v[102:105], v[80:81], off nt
	global_load_dwordx4 v[98:101], v[78:79], off nt
	v_lshl_add_u64 v[80:81], v[80:81], 0, s[4:5]
	v_lshl_add_u64 v[78:79], v[78:79], 0, s[4:5]
	global_load_dwordx4 v[94:97], v[78:79], off nt
	v_lshl_add_u64 v[78:79], v[80:81], 0, s[4:5]
	global_load_dwordx4 v[82:85], v[80:81], off nt
	s_nop 0
	global_load_dwordx4 v[78:81], v[78:79], off nt
	s_waitcnt vmcnt(16)
	s_mov_b32 s74, -1
	s_andn2_b64 vcc, exec, s[2:3]
	s_mov_b32 s4, s95
	s_mov_b32 s36, -1
	s_cbranch_vccnz .LBB0_767
	s_add_i32 s2, s40, 0xfffc
	s_and_b32 s3, s2, 0xff
	s_mulk_i32 s3, 0xab
	s_bfe_u32 s36, s3, 0x6000a
	s_mul_i32 s3, s36, 6
	s_sub_i32 s2, s2, s3
	s_and_b32 s3, s2, 0xff
	s_lshl_b32 s2, s2, 3
	s_and_b32 s2, s2, 0xf8
	s_sub_i32 s4, s2, 24
	s_cmp_lt_u32 s3, 3
	s_cselect_b32 s2, s2, s4
	s_cselect_b32 s74, 4, 16
	s_cselect_b32 s3, 2, 4
	s_add_i32 s2, s2, s79
	s_lshl_b32 s2, s2, s3
	s_sub_i32 s4, s2, s36

; #define LAS __attribute__((address_space(3)))
; __device__ __forceinline__ float row16_sum(float v) { v += dppf<0xB1>(v); v += dppf<0x4E>(v); v += dppf<0x141>(v); v += dppf<0x128>(v); return v; }
; __device__ __forceinline__ float dot4(f32x4 a, f32x4 b) { return (a.x * b.x + a.y * b.y) + (a.z * b.z + a.w * b.w); }
; __device__ __forceinline__ float wgt(int delta, int qpos) {
;     const int w = (delta <= 128 ? 1 : 0) + ((((delta & 3) == 0) && delta <= 512) ? 1 : 0) + ((((delta & 15) == 0) && delta <= 2048) ? 1 : 0);
;     return ((unsigned)delta <= (unsigned)qpos) ? (float)w : 0.f;
; }
; __device__ __forceinline__ void c_row_t(const f32x4 k, const f32x4 v, int delta, const f32x4 qa, float negb, f32x4& a, float& l) {
;     const float w = wgt(delta, 1 << 30);
;     const float d = row16_sum(dot4(k, qa));
;     const float p = w * __builtin_amdgcn_exp2f(d + negb);
;     l += p; a += v * p;
; }
; __device__ __forceinline__ void c_issue(CBuf& B, const float* kbase, const float* vbase, long rstride, int off) {
; #pragma unroll
;     for (int q = 0; q < 8; ++q) { B.k[q] = __builtin_nontemporal_load((const f32x4*)(kbase + (long)q * rstride + off)); B.v[q] = __builtin_nontemporal_load((const f32x4*)(vbase + (long)q * rstride + off)); }
; }
; __device__ __forceinline__ void c_consume(const CBuf& B, int delta0, int dstep, int tsel, const LAS float* qs, int off, float negb, CState& S) {
; #pragma unroll
;     for (int t = 0; t < 4; ++t) { if (tsel < 0 || tsel == t) {
;         const f32x4 qa = *(const LAS f32x4*)(qs + t * 512 + off);
; #pragma unroll
;         for (int q = 0; q < 8; ++q) c_row_t(B.k[q], B.v[q], delta0 + q * dstep + t, qa, negb, S.a[t], S.l[t]); } }
; }
.LBB0_779:
	s_lshl_b64 s[4:5], s[10:11], 11
	v_lshl_add_u64 v[22:23], v[160:161], 0, s[4:5]
	v_lshl_add_u64 v[26:27], v[162:163], 0, s[4:5]
	s_lshl_b64 s[2:3], s[2:3], 2
	v_lshl_add_u64 v[30:31], v[22:23], 0, s[2:3]
	v_lshl_add_u64 v[34:35], v[26:27], 0, s[2:3]
	v_lshl_add_u64 v[36:37], v[30:31], 0, s[2:3]
	v_lshl_add_u64 v[42:43], v[34:35], 0, s[2:3]
	v_lshl_add_u64 v[46:47], v[36:37], 0, s[2:3]
	v_lshl_add_u64 v[50:51], v[42:43], 0, s[2:3]
	v_lshl_add_u64 v[54:55], v[46:47], 0, s[2:3]
	s_waitcnt vmcnt(20)
	v_lshl_add_u64 v[58:59], v[50:51], 0, s[2:3]
	s_waitcnt vmcnt(19)
	v_lshl_add_u64 v[62:63], v[54:55], 0, s[2:3]
	s_waitcnt vmcnt(17)
	v_lshl_add_u64 v[66:67], v[58:59], 0, s[2:3]
	v_lshl_add_u64 v[70:71], v[62:63], 0, s[2:3]
	s_waitcnt vmcnt(16)
	v_lshl_add_u64 v[74:75], v[66:67], 0, s[2:3]
	global_load_dwordx4 v[14:17], v[22:23], off nt
	global_load_dwordx4 v[18:21], v[26:27], off nt
	global_load_dwordx4 v[38:41], v[42:43], off nt
	s_nop 0
	global_load_dwordx4 v[22:25], v[30:31], off nt
	global_load_dwordx4 v[26:29], v[34:35], off nt
	global_load_dwordx4 v[42:45], v[50:51], off nt
	s_nop 0
	global_load_dwordx4 v[30:33], v[36:37], off nt
	global_load_dwordx4 v[50:53], v[58:59], off nt
	s_nop 0
	global_load_dwordx4 v[34:37], v[46:47], off nt
	global_load_dwordx4 v[58:61], v[66:67], off nt
	s_nop 0
	global_load_dwordx4 v[46:49], v[54:55], off nt
	global_load_dwordx4 v[66:69], v[74:75], off nt
	v_lshl_add_u64 v[74:75], v[74:75], 0, s[2:3]
	global_load_dwordx4 v[54:57], v[62:63], off nt
	s_nop 0
	global_load_dwordx4 v[62:65], v[70:71], off nt
	v_lshl_add_u64 v[70:71], v[70:71], 0, s[2:3]
	global_load_dwordx4 v[70:73], v[70:71], off nt
	s_nop 0
	global_load_dwordx4 v[74:77], v[74:75], off nt
	s_branch .LBB0_780
.Lc_dummy:
	global_load_dwordx4 v[180:183], v[160:161], off nt
	global_load_dwordx4 v[180:183], v[160:161], off nt
	global_load_dwordx4 v[180:183], v[160:161], off nt
	global_load_dwordx4 v[180:183], v[160:161], off nt
	global_load_dwordx4 v[180:183], v[160:161], off nt
	global_load_dwordx4 v[180:183], v[160:161], off nt
	global_load_dwordx4 v[180:183], v[160:161], off nt
	global_load_dwordx4 v[180:183], v[160:161], off nt
	global_load_dwordx4 v[180:183], v[160:161], off nt
	global_load_dwordx4 v[180:183], v[160:161], off nt
	global_load_dwordx4 v[180:183], v[160:161], off nt
	global_load_dwordx4 v[180:183], v[160:161], off nt
	global_load_dwordx4 v[180:183], v[160:161], off nt
	global_load_dwordx4 v[180:183], v[160:161], off nt
	global_load_dwordx4 v[180:183], v[160:161], off nt
	global_load_dwordx4 v[180:183], v[160:161], off nt
.LBB0_780:
	s_cmp_gt_i32 s72, 0
	s_mul_i32 s70, s71, 3
	s_mul_i32 s74, s71, 5
	s_mul_i32 s10, s71, 6
	s_mul_i32 s40, s71, 7
	s_cbranch_scc1 .LBB0_782
	ds_read_b128 v[150:153], v164
	s_cmpk_lt_i32 s84, 0x81
	s_cselect_b64 s[2:3], -1, 0
	s_cmpk_lt_i32 s84, 0x201
	v_cndmask_b32_e64 v4, 0, 1, s[2:3]
	s_cselect_b64 s[80:81], -1, 0
	s_and_b32 s2, s84, 15
	s_waitcnt vmcnt(31) lgkmcnt(0)
	v_pk_mul_f32 v[168:169], v[148:149], v[152:153]
	v_pk_mul_f32 v[170:171], v[146:147], v[150:151]
	s_cmp_eq_u32 s2, 0
	v_pk_mov_b32 v[172:173], v[170:171], v[168:169] op_sel:[1,0]
	v_mov_b32_e32 v171, v169
	s_cselect_b64 s[2:3], -1, 0
	s_cmpk_lt_i32 s84, 0x801
	v_pk_add_f32 v[168:169], v[172:173], v[170:171]
	s_cselect_b64 s[4:5], -1, 0
	v_add_f32_e32 v2, v168, v169
	s_and_b64 vcc, s[4:5], s[2:3]
	s_cmp_lt_u32 s84, 0x40000001
	v_add_f32_dpp v2, v2, v2 quad_perm:[1,0,3,2] row_mask:0xf bank_mask:0xf bound_ctrl:1
	s_cselect_b64 s[2:3], -1, 0
	s_add_i32 s9, s71, s84
	v_add_f32_dpp v2, v2, v2 quad_perm:[2,3,0,1] row_mask:0xf bank_mask:0xf bound_ctrl:1
	s_cmpk_lt_i32 s9, 0x81
	s_cselect_b64 s[4:5], -1, 0
	v_add_f32_dpp v2, v2, v2 row_half_mirror row_mask:0xf bank_mask:0xf bound_ctrl:1
	s_waitcnt vmcnt(29)
	v_pk_mul_f32 v[170:171], v[142:143], v[150:151]
	s_mov_b32 s43, s42
	v_add_f32_dpp v2, v2, v2 row_ror:8 row_mask:0xf bank_mask:0xf bound_ctrl:1
	v_add_f32_e32 v2, s52, v2
	v_exp_f32_e32 v167, v2
	v_cndmask_b32_e64 v2, 0, 1, s[4:5]
	s_and_b32 s4, s9, 3
	s_cmp_eq_u32 s4, 0
	s_cselect_b64 s[4:5], -1, 0
	s_cmpk_lt_i32 s9, 0x201
	s_cselect_b64 s[6:7], -1, 0
	s_and_b64 s[4:5], s[6:7], s[4:5]
	v_cndmask_b32_e64 v168, 0, 1, s[4:5]
	s_and_b32 s4, s9, 15
	s_cmp_eq_u32 s4, 0
	s_cselect_b64 s[4:5], -1, 0
	s_cmpk_lt_i32 s9, 0x801
	s_cselect_b64 s[6:7], -1, 0
	s_and_b64 s[4:5], s[6:7], s[4:5]
	v_addc_co_u32_e64 v2, s[4:5], v168, v2, s[4:5]
	v_pk_mul_f32 v[168:169], v[144:145], v[152:153]
	s_cmp_lt_u32 s9, 0x40000001
	v_pk_mov_b32 v[172:173], v[170:171], v[168:169] op_sel:[1,0]
	v_mov_b32_e32 v171, v169
	v_pk_add_f32 v[168:169], v[172:173], v[170:171]
	v_cvt_f32_ubyte0_e32 v2, v2
	s_cselect_b64 s[4:5], -1, 0
	v_add_f32_e32 v168, v168, v169
	v_cndmask_b32_e64 v179, 0, v2, s[4:5]
	s_lshl_b32 s4, s71, 1
	v_add_f32_dpp v168, v168, v168 quad_perm:[1,0,3,2] row_mask:0xf bank_mask:0xf bound_ctrl:1
	s_add_i32 s7, s70, s84
	s_add_i32 s6, s4, s84
	v_add_f32_dpp v168, v168, v168 quad_perm:[2,3,0,1] row_mask:0xf bank_mask:0xf bound_ctrl:1
	s_cmpk_lt_i32 s7, 0x81
	s_cselect_b64 s[4:5], -1, 0
	v_add_f32_dpp v168, v168, v168 row_half_mirror row_mask:0xf bank_mask:0xf bound_ctrl:1
	s_cmpk_lt_i32 s6, 0x81
	s_mov_b32 s9, s8
	v_add_f32_dpp v168, v168, v168 row_ror:8 row_mask:0xf bank_mask:0xf bound_ctrl:1
	s_cselect_b64 s[36:37], -1, 0
	s_and_b64 s[38:39], s[6:7], s[8:9]
	v_add_f32_e32 v168, s52, v168
	s_cmp_eq_u32 s38, 0
	v_exp_f32_e32 v178, v168
	s_waitcnt vmcnt(27)
	v_pk_mul_f32 v[168:169], v[140:141], v[152:153]
	v_pk_mul_f32 v[170:171], v[138:139], v[150:151]
	s_cselect_b64 s[44:45], -1, 0
	s_cmp_eq_u32 s39, 0
	v_pk_mov_b32 v[172:173], v[170:171], v[168:169] op_sel:[1,0]
	v_mov_b32_e32 v171, v169
	s_cselect_b64 s[38:39], -1, 0
	s_cmpk_lt_i32 s6, 0x201
	v_pk_add_f32 v[168:169], v[172:173], v[170:171]
	s_waitcnt vmcnt(25)
; #define LAS __attribute__((address_space(3)))
; __device__ __forceinline__ float row16_sum(float v) { v += dppf<0xB1>(v); v += dppf<0x4E>(v); v += dppf<0x141>(v); v += dppf<0x128>(v); return v; }
; __device__ __forceinline__ float dot4(f32x4 a, f32x4 b) { return (a.x * b.x + a.y * b.y) + (a.z * b.z + a.w * b.w); }
; __device__ __forceinline__ float wgt(int delta, int qpos) {
;     const int w = (delta <= 128 ? 1 : 0) + ((((delta & 3) == 0) && delta <= 512) ? 1 : 0) + ((((delta & 15) == 0) && delta <= 2048) ? 1 : 0);
;     return ((unsigned)delta <= (unsigned)qpos) ? (float)w : 0.f;
; }
; __device__ __forceinline__ void c_row_t(const f32x4 k, const f32x4 v, int delta, const f32x4 qa, float negb, f32x4& a, float& l) {
;     const float w = wgt(delta, 1 << 30);
;     const float d = row16_sum(dot4(k, qa));
;     const float p = w * __builtin_amdgcn_exp2f(d + negb);
;     l += p; a += v * p;
; }
; __device__ __forceinline__ void c_issue(CBuf& B, const float* kbase, const float* vbase, long rstride, int off) {
; #pragma unroll
;     for (int q = 0; q < 8; ++q) { B.k[q] = __builtin_nontemporal_load((const f32x4*)(kbase + (long)q * rstride + off)); B.v[q] = __builtin_nontemporal_load((const f32x4*)(vbase + (long)q * rstride + off)); }
; }
; __device__ __forceinline__ void c_consume(const CBuf& B, int delta0, int dstep, int tsel, const LAS float* qs, int off, float negb, CState& S) {
; #pragma unroll
;     for (int t = 0; t < 4; ++t) { if (tsel < 0 || tsel == t) {
;         const f32x4 qa = *(const LAS f32x4*)(qs + t * 512 + off);
; #pragma unroll
;         for (int q = 0; q < 8; ++q) c_row_t(B.k[q], B.v[q], delta0 + q * dstep + t, qa, negb, S.a[t], S.l[t]); } }
; }
	v_pk_mul_f32 v[170:171], v[136:137], v[152:153]
	v_pk_mul_f32 v[172:173], v[134:135], v[150:151]
	s_cselect_b64 s[46:47], -1, 0
	s_cmpk_lt_i32 s7, 0x201
	v_pk_mov_b32 v[174:175], v[172:173], v[170:171] op_sel:[1,0]
	v_mov_b32_e32 v173, v171
	s_cselect_b64 s[48:49], -1, 0
	v_pk_add_f32 v[170:171], v[174:175], v[172:173]
	s_and_b64 s[44:45], s[46:47], s[44:45]
	s_and_b64 s[38:39], s[48:49], s[38:39]
	v_cndmask_b32_e64 v173, 0, 1, s[4:5]
	s_and_b64 s[4:5], s[6:7], s[42:43]
	s_cmp_eq_u32 s5, 0
	v_add_f32_e32 v168, v168, v169
	v_add_f32_e32 v169, v170, v171
	v_cndmask_b32_e64 v172, 0, 1, s[36:37]
	s_cselect_b64 s[36:37], -1, 0
	s_cmp_eq_u32 s4, 0
	v_add_f32_dpp v168, v168, v168 quad_perm:[1,0,3,2] row_mask:0xf bank_mask:0xf bound_ctrl:1
	v_add_f32_dpp v169, v169, v169 quad_perm:[1,0,3,2] row_mask:0xf bank_mask:0xf bound_ctrl:1
	v_cndmask_b32_e64 v171, 0, 1, s[38:39]
	s_cselect_b64 s[38:39], -1, 0
	s_cmpk_lt_i32 s7, 0x801
	v_add_f32_dpp v168, v168, v168 quad_perm:[2,3,0,1] row_mask:0xf bank_mask:0xf bound_ctrl:1
	v_add_f32_dpp v169, v169, v169 quad_perm:[2,3,0,1] row_mask:0xf bank_mask:0xf bound_ctrl:1
	s_cselect_b64 s[4:5], -1, 0
	s_cmpk_lt_i32 s6, 0x801
	v_add_f32_dpp v168, v168, v168 row_half_mirror row_mask:0xf bank_mask:0xf bound_ctrl:1
	v_add_f32_dpp v169, v169, v169 row_half_mirror row_mask:0xf bank_mask:0xf bound_ctrl:1
	v_cndmask_b32_e64 v170, 0, 1, s[44:45]
	s_cselect_b64 s[44:45], -1, 0
	s_and_b64 s[4:5], s[4:5], s[36:37]
	v_add_f32_dpp v168, v168, v168 row_ror:8 row_mask:0xf bank_mask:0xf bound_ctrl:1
	v_add_f32_dpp v169, v169, v169 row_ror:8 row_mask:0xf bank_mask:0xf bound_ctrl:1
	v_addc_co_u32_e64 v171, s[4:5], v171, v173, s[4:5]
	v_add_f32_e32 v168, s52, v168
	v_add_f32_e32 v169, s52, v169
	s_and_b64 s[4:5], s[44:45], s[38:39]
	v_exp_f32_e32 v168, v168
	v_exp_f32_e32 v169, v169
	v_addc_co_u32_e64 v170, s[4:5], v170, v172, s[4:5]
	s_cmp_lt_u32 s6, 0x40000001
	v_cvt_f32_ubyte0_e32 v170, v170
	s_cselect_b64 s[4:5], -1, 0
	s_cmp_lt_u32 s7, 0x40000001
	v_cvt_f32_ubyte0_e32 v171, v171
	s_cselect_b64 s[6:7], -1, 0
	v_cndmask_b32_e64 v170, 0, v170, s[4:5]
	s_add_i32 s5, s74, s84
	v_cndmask_b32_e64 v171, 0, v171, s[6:7]
	s_lshl_b32 s4, s71, 2
	s_mov_b32 s85, s5
	v_pk_mul_f32 v[168:169], v[170:171], v[168:169]
	s_waitcnt vmcnt(23)
	v_pk_mul_f32 v[170:171], v[132:133], v[152:153]
	v_pk_mul_f32 v[172:173], v[130:131], v[150:151]
	s_add_i32 s4, s4, s84
	s_and_b64 s[6:7], s[84:85], s[8:9]
	v_pk_mov_b32 v[174:175], v[172:173], v[170:171] op_sel:[1,0]
	v_mov_b32_e32 v173, v171
	s_cmp_eq_u32 s7, 0
	v_pk_add_f32 v[170:171], v[174:175], v[172:173]
	s_waitcnt vmcnt(21)
	v_pk_mul_f32 v[172:173], v[128:129], v[152:153]
	v_pk_mul_f32 v[174:175], v[126:127], v[150:151]
	s_cselect_b64 s[36:37], -1, 0
	s_cmp_eq_u32 s6, 0
	v_pk_mov_b32 v[176:177], v[174:175], v[172:173] op_sel:[1,0]
	v_mov_b32_e32 v175, v173
	s_cselect_b64 s[6:7], -1, 0
	v_pk_add_f32 v[172:173], v[176:177], v[174:175]
	s_and_b64 s[38:39], s[80:81], s[6:7]
	v_add_f32_e32 v170, v170, v171
	v_add_f32_e32 v171, v172, v173
	v_cndmask_b32_e64 v172, 0, 1, s[38:39]
	v_addc_co_u32_e32 v4, vcc, v172, v4, vcc
	v_cvt_f32_ubyte0_e32 v4, v4
	v_cndmask_b32_e64 v172, 0, v4, s[2:3]
	s_cmpk_lt_i32 s5, 0x81
	v_mul_f32_e32 v4, v172, v167
	s_cselect_b64 s[2:3], -1, 0
	s_cmpk_lt_i32 s4, 0x81
	v_mul_f32_e32 v2, v179, v178
	v_pk_fma_f32 v[86:87], v[118:119], v[4:5], v[86:87] op_sel_hi:[1,0,1]
	v_pk_fma_f32 v[88:89], v[120:121], v[4:5], v[88:89] op_sel_hi:[1,0,1]
	s_cselect_b64 s[38:39], -1, 0
	s_cmpk_lt_i32 s4, 0x201
	v_fmac_f32_e32 v157, v172, v167
	v_pk_fma_f32 v[88:89], v[124:125], v[2:3], v[88:89] op_sel_hi:[1,0,1]
	v_pk_fma_f32 v[86:87], v[122:123], v[2:3], v[86:87] op_sel_hi:[1,0,1]
	s_cselect_b64 s[44:45], -1, 0
	s_cmpk_lt_i32 s5, 0x201
	v_fmac_f32_e32 v157, v179, v178
	v_pk_fma_f32 v[86:87], v[114:115], v[168:169], v[86:87] op_sel_hi:[1,0,1]
	v_pk_fma_f32 v[88:89], v[116:117], v[168:169], v[88:89] op_sel_hi:[1,0,1]
	s_cselect_b64 s[46:47], -1, 0
	s_and_b64 s[6:7], s[44:45], s[6:7]
	v_add_f32_e32 v2, v157, v168
	v_pk_fma_f32 v[88:89], v[112:113], v[168:169], v[88:89] op_sel:[0,1,0]
	v_pk_fma_f32 v[86:87], v[110:111], v[168:169], v[86:87] op_sel:[0,1,0]
	v_cndmask_b32_e64 v4, 0, 1, s[6:7]
	s_and_b64 s[6:7], s[46:47], s[36:37]
	v_cndmask_b32_e64 v168, 0, 1, s[2:3]
	s_and_b64 s[2:3], s[4:5], s[42:43]
	s_cmp_eq_u32 s3, 0
	v_cndmask_b32_e64 v157, 0, 1, s[6:7]
	s_cselect_b64 s[6:7], -1, 0
	s_cmp_eq_u32 s2, 0
	v_add_f32_dpp v170, v170, v170 quad_perm:[1,0,3,2] row_mask:0xf bank_mask:0xf bound_ctrl:1
	v_add_f32_dpp v171, v171, v171 quad_perm:[1,0,3,2] row_mask:0xf bank_mask:0xf bound_ctrl:1
	s_cselect_b64 s[2:3], -1, 0
	s_cmpk_lt_i32 s5, 0x801
	v_add_f32_dpp v170, v170, v170 quad_perm:[2,3,0,1] row_mask:0xf bank_mask:0xf bound_ctrl:1
	v_add_f32_dpp v171, v171, v171 quad_perm:[2,3,0,1] row_mask:0xf bank_mask:0xf bound_ctrl:1
	s_cselect_b64 s[36:37], -1, 0
	s_cmpk_lt_i32 s4, 0x801
	v_add_f32_dpp v170, v170, v170 row_half_mirror row_mask:0xf bank_mask:0xf bound_ctrl:1
	v_add_f32_dpp v171, v171, v171 row_half_mirror row_mask:0xf bank_mask:0xf bound_ctrl:1
	v_cndmask_b32_e64 v167, 0, 1, s[38:39]
	s_cselect_b64 s[38:39], -1, 0
	s_and_b64 vcc, s[36:37], s[6:7]
	v_add_f32_dpp v170, v170, v170 row_ror:8 row_mask:0xf bank_mask:0xf bound_ctrl:1
	v_add_f32_dpp v171, v171, v171 row_ror:8 row_mask:0xf bank_mask:0xf bound_ctrl:1
	v_addc_co_u32_e32 v157, vcc, v157, v168, vcc
	v_add_f32_e32 v170, s52, v170
	v_add_f32_e32 v171, s52, v171
	s_and_b64 vcc, s[38:39], s[2:3]
	v_exp_f32_e32 v170, v170
	v_exp_f32_e32 v171, v171
	v_addc_co_u32_e32 v4, vcc, v4, v167, vcc
	s_cmp_lt_u32 s4, 0x40000001
	s_cselect_b64 vcc, -1, 0
	s_cmp_lt_u32 s5, 0x40000001
	v_cvt_f32_ubyte0_e32 v4, v4
	v_cvt_f32_ubyte0_e32 v157, v157
	s_cselect_b64 s[2:3], -1, 0
	v_add_f32_e32 v2, v2, v169
	v_cndmask_b32_e64 v169, 0, v157, s[2:3]
	v_cndmask_b32_e32 v168, 0, v4, vcc
	v_pk_mul_f32 v[168:169], v[168:169], v[170:171]
	s_waitcnt vmcnt(19)
; #define LAS __attribute__((address_space(3)))
; __device__ __forceinline__ float row16_sum(float v) { v += dppf<0xB1>(v); v += dppf<0x4E>(v); v += dppf<0x141>(v); v += dppf<0x128>(v); return v; }
; __device__ __forceinline__ float dot4(f32x4 a, f32x4 b) { return (a.x * b.x + a.y * b.y) + (a.z * b.z + a.w * b.w); }
; __device__ __forceinline__ float wgt(int delta, int qpos) {
;     const int w = (delta <= 128 ? 1 : 0) + ((((delta & 3) == 0) && delta <= 512) ? 1 : 0) + ((((delta & 15) == 0) && delta <= 2048) ? 1 : 0);
;     return ((unsigned)delta <= (unsigned)qpos) ? (float)w : 0.f;
; }
; __device__ __forceinline__ void c_row_t(const f32x4 k, const f32x4 v, int delta, const f32x4 qa, float negb, f32x4& a, float& l) {
;     const float w = wgt(delta, 1 << 30);
;     const float d = row16_sum(dot4(k, qa));
;     const float p = w * __builtin_amdgcn_exp2f(d + negb);
;     l += p; a += v * p;
; }
; __device__ __forceinline__ void c_issue(CBuf& B, const float* kbase, const float* vbase, long rstride, int off) {
; #pragma unroll
;     for (int q = 0; q < 8; ++q) { B.k[q] = __builtin_nontemporal_load((const f32x4*)(kbase + (long)q * rstride + off)); B.v[q] = __builtin_nontemporal_load((const f32x4*)(vbase + (long)q * rstride + off)); }
; }
; __device__ __forceinline__ void c_consume(const CBuf& B, int delta0, int dstep, int tsel, const LAS float* qs, int off, float negb, CState& S) {
; #pragma unroll
;     for (int t = 0; t < 4; ++t) { if (tsel < 0 || tsel == t) {
;         const f32x4 qa = *(const LAS f32x4*)(qs + t * 512 + off);
; #pragma unroll
;         for (int q = 0; q < 8; ++q) c_row_t(B.k[q], B.v[q], delta0 + q * dstep + t, qa, negb, S.a[t], S.l[t]); } }
; }
	v_pk_mul_f32 v[170:171], v[98:99], v[150:151]
	v_add_f32_e32 v2, v2, v168
	v_pk_fma_f32 v[86:87], v[106:107], v[168:169], v[86:87] op_sel_hi:[1,0,1]
	v_pk_fma_f32 v[88:89], v[108:109], v[168:169], v[88:89] op_sel_hi:[1,0,1]
	v_add_f32_e32 v2, v2, v169
	v_pk_fma_f32 v[88:89], v[104:105], v[168:169], v[88:89] op_sel:[0,1,0]
	v_pk_fma_f32 v[86:87], v[102:103], v[168:169], v[86:87] op_sel:[0,1,0]
	v_pk_mul_f32 v[168:169], v[100:101], v[152:153]
	s_add_i32 s3, s40, s84
	v_pk_mov_b32 v[172:173], v[170:171], v[168:169] op_sel:[1,0]
	v_mov_b32_e32 v171, v169
	s_add_i32 s2, s10, s84
	v_pk_add_f32 v[168:169], v[172:173], v[170:171]
	s_cmpk_lt_i32 s3, 0x81
	v_add_f32_e32 v4, v168, v169
	s_cselect_b64 s[4:5], -1, 0
	s_cmpk_lt_i32 s2, 0x81
	v_add_f32_dpp v4, v4, v4 quad_perm:[1,0,3,2] row_mask:0xf bank_mask:0xf bound_ctrl:1
	s_cselect_b64 s[6:7], -1, 0
	s_and_b64 s[36:37], s[2:3], s[8:9]
	v_add_f32_dpp v4, v4, v4 quad_perm:[2,3,0,1] row_mask:0xf bank_mask:0xf bound_ctrl:1
	s_cmp_eq_u32 s36, 0
	s_waitcnt vmcnt(18)
	v_pk_mul_f32 v[152:153], v[96:97], v[152:153]
	v_add_f32_dpp v4, v4, v4 row_half_mirror row_mask:0xf bank_mask:0xf bound_ctrl:1
	v_pk_mul_f32 v[150:151], v[94:95], v[150:151]
	s_cselect_b64 s[38:39], -1, 0
	s_cmp_eq_u32 s37, 0
	v_add_f32_dpp v4, v4, v4 row_ror:8 row_mask:0xf bank_mask:0xf bound_ctrl:1
	v_pk_mov_b32 v[170:171], v[150:151], v[152:153] op_sel:[1,0]
	v_mov_b32_e32 v151, v153
	s_cselect_b64 s[36:37], -1, 0
	s_cmpk_lt_i32 s2, 0x201
	v_add_f32_e32 v4, s52, v4
	v_pk_add_f32 v[150:151], v[170:171], v[150:151]
	s_cselect_b64 s[44:45], -1, 0
	s_cmpk_lt_i32 s3, 0x201
	v_exp_f32_e32 v168, v4
	v_add_f32_e32 v4, v150, v151
	s_cselect_b64 s[46:47], -1, 0
	s_and_b64 s[38:39], s[44:45], s[38:39]
	v_add_f32_dpp v4, v4, v4 quad_perm:[1,0,3,2] row_mask:0xf bank_mask:0xf bound_ctrl:1
	s_and_b64 s[36:37], s[46:47], s[36:37]
	v_cndmask_b32_e64 v152, 0, 1, s[4:5]
	s_and_b64 s[4:5], s[2:3], s[42:43]
	v_add_f32_dpp v4, v4, v4 quad_perm:[2,3,0,1] row_mask:0xf bank_mask:0xf bound_ctrl:1
	s_cmp_eq_u32 s5, 0
	v_cndmask_b32_e64 v151, 0, 1, s[6:7]
	v_add_f32_dpp v4, v4, v4 row_half_mirror row_mask:0xf bank_mask:0xf bound_ctrl:1
	s_cselect_b64 s[6:7], -1, 0
	s_cmp_eq_u32 s4, 0
	v_add_f32_dpp v4, v4, v4 row_ror:8 row_mask:0xf bank_mask:0xf bound_ctrl:1
	s_cselect_b64 s[4:5], -1, 0
	s_cmpk_lt_i32 s3, 0x801
	v_add_f32_e32 v4, s52, v4
	v_cndmask_b32_e64 v150, 0, 1, s[36:37]
	s_cselect_b64 s[36:37], -1, 0
	s_cmpk_lt_i32 s2, 0x801
	v_exp_f32_e32 v169, v4
	v_cndmask_b32_e64 v4, 0, 1, s[38:39]
	s_cselect_b64 s[38:39], -1, 0
	s_and_b64 vcc, s[36:37], s[6:7]
	v_addc_co_u32_e32 v150, vcc, v150, v152, vcc
	s_and_b64 vcc, s[38:39], s[4:5]
	s_nop 0
	v_addc_co_u32_e32 v4, vcc, v4, v151, vcc
	s_cmp_lt_u32 s2, 0x40000001
	s_cselect_b64 vcc, -1, 0
	s_cmp_lt_u32 s3, 0x40000001
	v_cvt_f32_ubyte0_e32 v4, v4
	v_cvt_f32_ubyte0_e32 v150, v150
	s_cselect_b64 s[2:3], -1, 0
	v_cndmask_b32_e64 v151, 0, v150, s[2:3]
	v_cndmask_b32_e32 v150, 0, v4, vcc
	v_pk_mul_f32 v[150:151], v[150:151], v[168:169]
	s_nop 0
	v_add_f32_e32 v2, v2, v150
	s_waitcnt vmcnt(17)
	v_pk_fma_f32 v[86:87], v[82:83], v[150:151], v[86:87] op_sel_hi:[1,0,1]
	v_pk_fma_f32 v[88:89], v[84:85], v[150:151], v[88:89] op_sel_hi:[1,0,1]
	v_add_f32_e32 v157, v2, v151
	s_waitcnt vmcnt(16)
	v_pk_fma_f32 v[88:89], v[80:81], v[150:151], v[88:89] op_sel:[0,1,0]
	v_pk_fma_f32 v[86:87], v[78:79], v[150:151], v[86:87] op_sel:[0,1,0]
.LBB0_782:
	s_cmp_lt_i32 s72, 0
	s_cselect_b64 s[4:5], -1, 0
	s_cmp_gt_i32 s72, -1
	s_cselect_b64 s[2:3], -1, 0
	s_cmp_lg_u32 s72, 1
	s_cselect_b64 s[6:7], -1, 0
	s_and_b64 s[2:3], s[2:3], s[6:7]
	s_and_b64 vcc, exec, s[2:3]
	s_cbranch_vccnz .LBB0_784
	ds_read_b128 v[150:153], v164 offset:2048
	s_add_i32 s6, s84, 1
	s_add_i32 s81, s74, s6
	s_lshl_b32 s2, s71, 2
	s_mov_b32 s7, s81
	s_waitcnt vmcnt(31) lgkmcnt(0)
	v_pk_mul_f32 v[168:169], v[148:149], v[152:153]
	v_pk_mul_f32 v[170:171], v[146:147], v[150:151]
	s_waitcnt vmcnt(29)
	v_pk_mul_f32 v[172:173], v[144:145], v[152:153]
	v_pk_mov_b32 v[176:177], v[170:171], v[168:169] op_sel:[1,0]
	v_mov_b32_e32 v171, v169
	v_pk_add_f32 v[168:169], v[176:177], v[170:171]
	v_pk_mul_f32 v[174:175], v[142:143], v[150:151]
	v_add_f32_e32 v2, v168, v169
	v_pk_mov_b32 v[170:171], v[174:175], v[172:173] op_sel:[1,0]
	v_mov_b32_e32 v175, v173
	v_add_f32_dpp v2, v2, v2 quad_perm:[1,0,3,2] row_mask:0xf bank_mask:0xf bound_ctrl:1
	v_pk_add_f32 v[170:171], v[170:171], v[174:175]
	s_waitcnt vmcnt(27)
	v_pk_mul_f32 v[172:173], v[138:139], v[150:151]
	v_add_f32_dpp v2, v2, v2 quad_perm:[2,3,0,1] row_mask:0xf bank_mask:0xf bound_ctrl:1
	s_mov_b32 s9, s8
	s_lshl_b32 s48, s71, 1
	v_add_f32_dpp v2, v2, v2 row_half_mirror row_mask:0xf bank_mask:0xf bound_ctrl:1
	s_add_i32 s80, s2, s6
	s_and_b64 s[2:3], s[6:7], s[8:9]
	v_add_f32_dpp v2, v2, v2 row_ror:8 row_mask:0xf bank_mask:0xf bound_ctrl:1
	v_add_f32_e32 v2, s52, v2
	v_exp_f32_e32 v168, v2
	v_add_f32_e32 v2, v170, v171
	v_pk_mul_f32 v[170:171], v[140:141], v[152:153]
	s_cmp_eq_u32 s3, 0
	v_add_f32_dpp v2, v2, v2 quad_perm:[1,0,3,2] row_mask:0xf bank_mask:0xf bound_ctrl:1
	v_pk_mov_b32 v[174:175], v[172:173], v[170:171] op_sel:[1,0]
	v_mov_b32_e32 v173, v171
	v_add_f32_dpp v2, v2, v2 quad_perm:[2,3,0,1] row_mask:0xf bank_mask:0xf bound_ctrl:1
	v_pk_add_f32 v[170:171], v[174:175], v[172:173]
	s_waitcnt vmcnt(25)
	v_pk_mul_f32 v[172:173], v[136:137], v[152:153]
	v_add_f32_dpp v2, v2, v2 row_half_mirror row_mask:0xf bank_mask:0xf bound_ctrl:1
	v_pk_mul_f32 v[174:175], v[134:135], v[150:151]
	s_cselect_b64 s[76:77], -1, 0
	v_add_f32_dpp v2, v2, v2 row_ror:8 row_mask:0xf bank_mask:0xf bound_ctrl:1
	v_add_f32_e32 v2, s52, v2
	v_exp_f32_e32 v169, v2
	v_add_f32_e32 v2, v170, v171
	v_pk_mov_b32 v[176:177], v[174:175], v[172:173] op_sel:[1,0]
	v_mov_b32_e32 v175, v173
	v_add_f32_dpp v2, v2, v2 quad_perm:[1,0,3,2] row_mask:0xf bank_mask:0xf bound_ctrl:1
	v_pk_add_f32 v[172:173], v[176:177], v[174:175]
	s_waitcnt vmcnt(23)
; #define LAS __attribute__((address_space(3)))
; __device__ __forceinline__ float row16_sum(float v) { v += dppf<0xB1>(v); v += dppf<0x4E>(v); v += dppf<0x141>(v); v += dppf<0x128>(v); return v; }
; __device__ __forceinline__ float dot4(f32x4 a, f32x4 b) { return (a.x * b.x + a.y * b.y) + (a.z * b.z + a.w * b.w); }
; __device__ __forceinline__ float wgt(int delta, int qpos) {
;     const int w = (delta <= 128 ? 1 : 0) + ((((delta & 3) == 0) && delta <= 512) ? 1 : 0) + ((((delta & 15) == 0) && delta <= 2048) ? 1 : 0);
;     return ((unsigned)delta <= (unsigned)qpos) ? (float)w : 0.f;
; }
; __device__ __forceinline__ void c_row_t(const f32x4 k, const f32x4 v, int delta, const f32x4 qa, float negb, f32x4& a, float& l) {
;     const float w = wgt(delta, 1 << 30);
;     const float d = row16_sum(dot4(k, qa));
;     const float p = w * __builtin_amdgcn_exp2f(d + negb);
;     l += p; a += v * p;
; }
; __device__ __forceinline__ void c_issue(CBuf& B, const float* kbase, const float* vbase, long rstride, int off) {
; #pragma unroll
;     for (int q = 0; q < 8; ++q) { B.k[q] = __builtin_nontemporal_load((const f32x4*)(kbase + (long)q * rstride + off)); B.v[q] = __builtin_nontemporal_load((const f32x4*)(vbase + (long)q * rstride + off)); }
; }
; __device__ __forceinline__ void c_consume(const CBuf& B, int delta0, int dstep, int tsel, const LAS float* qs, int off, float negb, CState& S) {
; #pragma unroll
;     for (int t = 0; t < 4; ++t) { if (tsel < 0 || tsel == t) {
;         const f32x4 qa = *(const LAS f32x4*)(qs + t * 512 + off);
; #pragma unroll
;         for (int q = 0; q < 8; ++q) c_row_t(B.k[q], B.v[q], delta0 + q * dstep + t, qa, negb, S.a[t], S.l[t]); } }
; }
	v_pk_mul_f32 v[174:175], v[130:131], v[150:151]
	v_add_f32_dpp v2, v2, v2 quad_perm:[2,3,0,1] row_mask:0xf bank_mask:0xf bound_ctrl:1
	s_cmp_eq_u32 s2, 0
	s_cselect_b64 s[92:93], -1, 0
	v_add_f32_dpp v2, v2, v2 row_half_mirror row_mask:0xf bank_mask:0xf bound_ctrl:1
	s_add_i32 s7, s6, s71
	s_cmpk_lt_i32 s7, 0x81
	v_add_f32_dpp v2, v2, v2 row_ror:8 row_mask:0xf bank_mask:0xf bound_ctrl:1
	v_add_f32_e32 v2, s52, v2
	v_exp_f32_e32 v170, v2
	v_add_f32_e32 v2, v172, v173
	v_pk_mul_f32 v[172:173], v[132:133], v[152:153]
	s_cselect_b64 s[2:3], -1, 0
	v_add_f32_dpp v2, v2, v2 quad_perm:[1,0,3,2] row_mask:0xf bank_mask:0xf bound_ctrl:1
	v_pk_mov_b32 v[176:177], v[174:175], v[172:173] op_sel:[1,0]
	v_mov_b32_e32 v175, v173
	v_add_f32_dpp v2, v2, v2 quad_perm:[2,3,0,1] row_mask:0xf bank_mask:0xf bound_ctrl:1
	v_pk_add_f32 v[172:173], v[176:177], v[174:175]
	s_cmpk_lt_i32 s6, 0x81
	v_add_f32_dpp v2, v2, v2 row_half_mirror row_mask:0xf bank_mask:0xf bound_ctrl:1
	s_cselect_b64 s[36:37], -1, 0
	s_and_b32 s38, s7, 3
	v_add_f32_dpp v2, v2, v2 row_ror:8 row_mask:0xf bank_mask:0xf bound_ctrl:1
	v_add_f32_e32 v2, s52, v2
	v_exp_f32_e32 v171, v2
	v_add_f32_e32 v2, v172, v173
	s_cmp_eq_u32 s38, 0
	s_waitcnt vmcnt(21)
	v_pk_mul_f32 v[174:175], v[128:129], v[152:153]
	v_add_f32_dpp v2, v2, v2 quad_perm:[1,0,3,2] row_mask:0xf bank_mask:0xf bound_ctrl:1
	v_pk_mul_f32 v[176:177], v[126:127], v[150:151]
	s_cselect_b64 s[38:39], -1, 0
	v_add_f32_dpp v2, v2, v2 quad_perm:[2,3,0,1] row_mask:0xf bank_mask:0xf bound_ctrl:1
	s_cmpk_lt_i32 s7, 0x201
	v_pk_mov_b32 v[178:179], v[176:177], v[174:175] op_sel:[1,0]
	v_add_f32_dpp v2, v2, v2 row_half_mirror row_mask:0xf bank_mask:0xf bound_ctrl:1
	v_mov_b32_e32 v177, v175
	s_cselect_b64 s[44:45], -1, 0
	v_add_f32_dpp v2, v2, v2 row_ror:8 row_mask:0xf bank_mask:0xf bound_ctrl:1
	s_cmpk_lt_i32 s6, 0x201
	v_add_f32_e32 v2, s52, v2
	v_pk_add_f32 v[174:175], v[178:179], v[176:177]
	s_cselect_b64 s[46:47], -1, 0
	s_mov_b32 s43, s42
	v_exp_f32_e32 v172, v2
	v_add_f32_e32 v2, v174, v175
	s_and_b64 s[46:47], s[46:47], s[92:93]
	s_and_b64 s[38:39], s[44:45], s[38:39]
	v_cndmask_b32_e64 v174, 0, 1, s[2:3]
	s_and_b64 s[2:3], s[6:7], s[42:43]
	s_cmp_eq_u32 s3, 0
	v_add_f32_dpp v2, v2, v2 quad_perm:[1,0,3,2] row_mask:0xf bank_mask:0xf bound_ctrl:1
	v_cndmask_b32_e64 v167, 0, 1, s[36:37]
	s_cselect_b64 s[36:37], -1, 0
	s_cmp_eq_u32 s2, 0
	v_add_f32_dpp v2, v2, v2 quad_perm:[2,3,0,1] row_mask:0xf bank_mask:0xf bound_ctrl:1
	s_cselect_b64 s[2:3], -1, 0
	s_cmpk_lt_i32 s7, 0x801
	v_add_f32_dpp v2, v2, v2 row_half_mirror row_mask:0xf bank_mask:0xf bound_ctrl:1
	v_cndmask_b32_e64 v4, 0, 1, s[38:39]
	s_cselect_b64 s[38:39], -1, 0
	s_cmpk_lt_i32 s6, 0x801
	v_add_f32_dpp v2, v2, v2 row_ror:8 row_mask:0xf bank_mask:0xf bound_ctrl:1
	s_cselect_b64 s[44:45], -1, 0
	s_and_b64 vcc, s[38:39], s[36:37]
	v_add_f32_e32 v2, s52, v2
	v_addc_co_u32_e32 v4, vcc, v4, v174, vcc
	v_exp_f32_e32 v173, v2
	v_cndmask_b32_e64 v2, 0, 1, s[46:47]
	s_and_b64 vcc, s[44:45], s[2:3]
	v_addc_co_u32_e32 v2, vcc, v2, v167, vcc
	s_cmp_lt_u32 s84, 2.0
	s_cselect_b64 vcc, -1, 0
	s_cmp_lt_u32 s7, 0x40000001
	v_cvt_f32_ubyte0_e32 v4, v4
	s_cselect_b64 s[2:3], -1, 0
	v_cndmask_b32_e64 v175, 0, v4, s[2:3]
	s_add_i32 s3, s70, s6
	s_add_i32 s2, s48, s6
	s_cmpk_lt_i32 s3, 0x81
	s_cselect_b64 s[36:37], -1, 0
	s_cmpk_lt_i32 s2, 0x81
	s_cselect_b64 s[38:39], -1, 0
	s_and_b64 s[44:45], s[2:3], s[8:9]
	s_cmp_eq_u32 s44, 0
	v_cvt_f32_ubyte0_e32 v2, v2
	s_cselect_b64 s[46:47], -1, 0
	s_cmp_eq_u32 s45, 0
	v_cndmask_b32_e32 v174, 0, v2, vcc
	s_cselect_b64 s[44:45], -1, 0
	s_cmpk_lt_i32 s2, 0x201
	v_pk_mul_f32 v[168:169], v[174:175], v[168:169]
	s_cselect_b64 s[48:49], -1, 0
	s_cmpk_lt_i32 s3, 0x201
	v_pk_fma_f32 v[90:91], v[118:119], v[168:169], v[90:91] op_sel_hi:[1,0,1]
	v_pk_fma_f32 v[92:93], v[120:121], v[168:169], v[92:93] op_sel_hi:[1,0,1]
	s_cselect_b64 s[50:51], -1, 0
	v_add_f32_e32 v2, v166, v168
	v_pk_fma_f32 v[92:93], v[124:125], v[168:169], v[92:93] op_sel:[0,1,0]
	v_pk_fma_f32 v[90:91], v[122:123], v[168:169], v[90:91] op_sel:[0,1,0]
	s_and_b64 s[46:47], s[48:49], s[46:47]
	s_and_b64 s[44:45], s[50:51], s[44:45]
	v_cndmask_b32_e64 v168, 0, 1, s[36:37]
	s_and_b64 s[36:37], s[2:3], s[42:43]
	s_cmp_eq_u32 s37, 0
	v_cndmask_b32_e64 v167, 0, 1, s[38:39]
	s_cselect_b64 s[38:39], -1, 0
	s_cmp_eq_u32 s36, 0
	s_cselect_b64 s[36:37], -1, 0
	s_cmpk_lt_i32 s3, 0x801
	v_cndmask_b32_e64 v166, 0, 1, s[44:45]
	s_cselect_b64 s[44:45], -1, 0
	s_cmpk_lt_i32 s2, 0x801
	v_cndmask_b32_e64 v4, 0, 1, s[46:47]
	s_cselect_b64 s[46:47], -1, 0
	s_and_b64 vcc, s[44:45], s[38:39]
	v_addc_co_u32_e32 v166, vcc, v166, v168, vcc
	s_and_b64 vcc, s[46:47], s[36:37]
	s_nop 0
	v_addc_co_u32_e32 v4, vcc, v4, v167, vcc
	s_cmp_lt_u32 s2, 0x40000001
	s_cselect_b64 vcc, -1, 0
	s_cmp_lt_u32 s3, 0x40000001
	v_cvt_f32_ubyte0_e32 v166, v166
	s_cselect_b64 s[2:3], -1, 0
	s_cmpk_lt_i32 s81, 0x81
	v_cndmask_b32_e64 v167, 0, v166, s[2:3]
	s_cselect_b64 s[2:3], -1, 0
	s_cmpk_lt_i32 s80, 0x81
	s_cselect_b64 s[36:37], -1, 0
	s_cmpk_lt_i32 s80, 0x201
	v_cvt_f32_ubyte0_e32 v4, v4
	s_cselect_b64 s[38:39], -1, 0
	s_cmpk_lt_i32 s81, 0x201
	v_cndmask_b32_e32 v166, 0, v4, vcc
	s_cselect_b64 s[44:45], -1, 0
	s_and_b64 s[38:39], s[38:39], s[92:93]
	v_add_f32_e32 v2, v2, v169
	v_pk_mul_f32 v[166:167], v[166:167], v[170:171]
	v_cndmask_b32_e64 v4, 0, 1, s[38:39]
	s_and_b64 s[38:39], s[44:45], s[76:77]
	v_cndmask_b32_e64 v168, 0, 1, s[2:3]
	s_and_b64 s[2:3], s[80:81], s[42:43]
	v_add_f32_e32 v2, v2, v166
	v_pk_fma_f32 v[90:91], v[114:115], v[166:167], v[90:91] op_sel_hi:[1,0,1]
	v_pk_fma_f32 v[92:93], v[116:117], v[166:167], v[92:93] op_sel_hi:[1,0,1]
	s_cmp_eq_u32 s3, 0
	v_add_f32_e32 v2, v2, v167
	v_pk_fma_f32 v[92:93], v[112:113], v[166:167], v[92:93] op_sel:[0,1,0]
	v_pk_fma_f32 v[90:91], v[110:111], v[166:167], v[90:91] op_sel:[0,1,0]
	v_cndmask_b32_e64 v167, 0, 1, s[36:37]
	s_cselect_b64 s[36:37], -1, 0
	s_cmp_eq_u32 s2, 0
	s_cselect_b64 s[2:3], -1, 0
	s_cmpk_lt_i32 s81, 0x801
	v_cndmask_b32_e64 v166, 0, 1, s[38:39]
	s_cselect_b64 s[38:39], -1, 0
	s_cmpk_lt_i32 s80, 0x801
	s_cselect_b64 s[44:45], -1, 0
	s_and_b64 vcc, s[38:39], s[36:37]
	v_addc_co_u32_e32 v166, vcc, v166, v168, vcc
	s_and_b64 vcc, s[44:45], s[2:3]
	s_nop 0
	v_addc_co_u32_e32 v4, vcc, v4, v167, vcc
	s_cmp_lt_u32 s80, 0x40000001
	s_cselect_b64 vcc, -1, 0
	s_cmp_lt_u32 s81, 0x40000001
	v_cvt_f32_ubyte0_e32 v4, v4
	v_cvt_f32_ubyte0_e32 v166, v166
	s_cselect_b64 s[2:3], -1, 0
	v_cndmask_b32_e64 v167, 0, v166, s[2:3]
	v_cndmask_b32_e32 v166, 0, v4, vcc
	v_pk_mul_f32 v[166:167], v[166:167], v[172:173]
	s_waitcnt vmcnt(19)
; #define LAS __attribute__((address_space(3)))
; __device__ __forceinline__ float row16_sum(float v) { v += dppf<0xB1>(v); v += dppf<0x4E>(v); v += dppf<0x141>(v); v += dppf<0x128>(v); return v; }
; __device__ __forceinline__ float dot4(f32x4 a, f32x4 b) { return (a.x * b.x + a.y * b.y) + (a.z * b.z + a.w * b.w); }
; __device__ __forceinline__ float wgt(int delta, int qpos) {
;     const int w = (delta <= 128 ? 1 : 0) + ((((delta & 3) == 0) && delta <= 512) ? 1 : 0) + ((((delta & 15) == 0) && delta <= 2048) ? 1 : 0);
;     return ((unsigned)delta <= (unsigned)qpos) ? (float)w : 0.f;
; }
; __device__ __forceinline__ void c_row_t(const f32x4 k, const f32x4 v, int delta, const f32x4 qa, float negb, f32x4& a, float& l) {
;     const float w = wgt(delta, 1 << 30);
;     const float d = row16_sum(dot4(k, qa));
;     const float p = w * __builtin_amdgcn_exp2f(d + negb);
;     l += p; a += v * p;
; }
; __device__ __forceinline__ void c_issue(CBuf& B, const float* kbase, const float* vbase, long rstride, int off) {
; #pragma unroll
;     for (int q = 0; q < 8; ++q) { B.k[q] = __builtin_nontemporal_load((const f32x4*)(kbase + (long)q * rstride + off)); B.v[q] = __builtin_nontemporal_load((const f32x4*)(vbase + (long)q * rstride + off)); }
; }
; __device__ __forceinline__ void c_consume(const CBuf& B, int delta0, int dstep, int tsel, const LAS float* qs, int off, float negb, CState& S) {
; #pragma unroll
;     for (int t = 0; t < 4; ++t) { if (tsel < 0 || tsel == t) {
;         const f32x4 qa = *(const LAS f32x4*)(qs + t * 512 + off);
; #pragma unroll
;         for (int q = 0; q < 8; ++q) c_row_t(B.k[q], B.v[q], delta0 + q * dstep + t, qa, negb, S.a[t], S.l[t]); } }
; }
	v_pk_mul_f32 v[168:169], v[98:99], v[150:151]
	v_add_f32_e32 v2, v2, v166
	v_pk_fma_f32 v[90:91], v[106:107], v[166:167], v[90:91] op_sel_hi:[1,0,1]
	v_pk_fma_f32 v[92:93], v[108:109], v[166:167], v[92:93] op_sel_hi:[1,0,1]
	v_add_f32_e32 v2, v2, v167
	v_pk_fma_f32 v[92:93], v[104:105], v[166:167], v[92:93] op_sel:[0,1,0]
	v_pk_fma_f32 v[90:91], v[102:103], v[166:167], v[90:91] op_sel:[0,1,0]
	v_pk_mul_f32 v[166:167], v[100:101], v[152:153]
	s_add_i32 s3, s40, s6
	v_pk_mov_b32 v[170:171], v[168:169], v[166:167] op_sel:[1,0]
	v_mov_b32_e32 v169, v167
	s_add_i32 s2, s10, s6
	v_pk_add_f32 v[166:167], v[170:171], v[168:169]
	s_cmpk_lt_i32 s3, 0x81
	v_add_f32_e32 v4, v166, v167
	s_cselect_b64 s[6:7], -1, 0
	s_cmpk_lt_i32 s2, 0x81
	v_add_f32_dpp v4, v4, v4 quad_perm:[1,0,3,2] row_mask:0xf bank_mask:0xf bound_ctrl:1
	s_cselect_b64 s[36:37], -1, 0
	s_and_b64 s[38:39], s[2:3], s[8:9]
	v_add_f32_dpp v4, v4, v4 quad_perm:[2,3,0,1] row_mask:0xf bank_mask:0xf bound_ctrl:1
	s_cmp_eq_u32 s38, 0
	s_waitcnt vmcnt(18)
	v_pk_mul_f32 v[152:153], v[96:97], v[152:153]
	v_add_f32_dpp v4, v4, v4 row_half_mirror row_mask:0xf bank_mask:0xf bound_ctrl:1
	v_pk_mul_f32 v[150:151], v[94:95], v[150:151]
	s_cselect_b64 s[44:45], -1, 0
	s_cmp_eq_u32 s39, 0
	v_add_f32_dpp v4, v4, v4 row_ror:8 row_mask:0xf bank_mask:0xf bound_ctrl:1
	v_pk_mov_b32 v[168:169], v[150:151], v[152:153] op_sel:[1,0]
	v_mov_b32_e32 v151, v153
	s_cselect_b64 s[38:39], -1, 0
	s_cmpk_lt_i32 s2, 0x201
	v_add_f32_e32 v4, s52, v4
	v_pk_add_f32 v[150:151], v[168:169], v[150:151]
	s_cselect_b64 s[46:47], -1, 0
	s_cmpk_lt_i32 s3, 0x201
	v_exp_f32_e32 v166, v4
	v_add_f32_e32 v4, v150, v151
	s_cselect_b64 s[48:49], -1, 0
	s_and_b64 s[44:45], s[46:47], s[44:45]
	v_add_f32_dpp v4, v4, v4 quad_perm:[1,0,3,2] row_mask:0xf bank_mask:0xf bound_ctrl:1
	s_and_b64 s[38:39], s[48:49], s[38:39]
	v_cndmask_b32_e64 v152, 0, 1, s[6:7]
	s_and_b64 s[6:7], s[2:3], s[42:43]
	v_add_f32_dpp v4, v4, v4 quad_perm:[2,3,0,1] row_mask:0xf bank_mask:0xf bound_ctrl:1
	s_cmp_eq_u32 s7, 0
	v_cndmask_b32_e64 v151, 0, 1, s[36:37]
	v_add_f32_dpp v4, v4, v4 row_half_mirror row_mask:0xf bank_mask:0xf bound_ctrl:1
	s_cselect_b64 s[36:37], -1, 0
	s_cmp_eq_u32 s6, 0
	v_add_f32_dpp v4, v4, v4 row_ror:8 row_mask:0xf bank_mask:0xf bound_ctrl:1
	s_cselect_b64 s[6:7], -1, 0
	s_cmpk_lt_i32 s3, 0x801
	v_add_f32_e32 v4, s52, v4
	v_cndmask_b32_e64 v150, 0, 1, s[38:39]
	s_cselect_b64 s[38:39], -1, 0
	s_cmpk_lt_i32 s2, 0x801
	v_exp_f32_e32 v167, v4
	v_cndmask_b32_e64 v4, 0, 1, s[44:45]
	s_cselect_b64 s[44:45], -1, 0
	s_and_b64 vcc, s[38:39], s[36:37]
	v_addc_co_u32_e32 v150, vcc, v150, v152, vcc
	s_and_b64 vcc, s[44:45], s[6:7]
	s_nop 0
	v_addc_co_u32_e32 v4, vcc, v4, v151, vcc
	s_cmp_lt_u32 s2, 0x40000001
	s_cselect_b64 vcc, -1, 0
	s_cmp_lt_u32 s3, 0x40000001
	v_cvt_f32_ubyte0_e32 v4, v4
	v_cvt_f32_ubyte0_e32 v150, v150
	s_cselect_b64 s[2:3], -1, 0
	v_cndmask_b32_e64 v151, 0, v150, s[2:3]
	v_cndmask_b32_e32 v150, 0, v4, vcc
	v_pk_mul_f32 v[150:151], v[150:151], v[166:167]
	s_nop 0
	v_add_f32_e32 v2, v2, v150
	s_waitcnt vmcnt(17)
	v_pk_fma_f32 v[90:91], v[82:83], v[150:151], v[90:91] op_sel_hi:[1,0,1]
	v_pk_fma_f32 v[92:93], v[84:85], v[150:151], v[92:93] op_sel_hi:[1,0,1]
	v_add_f32_e32 v166, v2, v151
	s_waitcnt vmcnt(16)
	v_pk_fma_f32 v[92:93], v[80:81], v[150:151], v[92:93] op_sel:[0,1,0]
	v_pk_fma_f32 v[90:91], v[78:79], v[150:151], v[90:91] op_sel:[0,1,0]
.LBB0_784:
	s_cmp_lg_u32 s72, 2
	s_cselect_b64 s[2:3], -1, 0
	s_xor_b64 s[4:5], s[4:5], -1
	s_and_b64 s[2:3], s[4:5], s[2:3]
	s_and_b64 vcc, exec, s[2:3]
	s_cbranch_vccnz .LBB0_786
	ds_read_b128 v[150:153], v164 offset:4096
	s_add_i32 s6, s84, 2
	s_add_i32 s81, s74, s6
	s_lshl_b32 s2, s71, 2
	s_mov_b32 s7, s81
	s_waitcnt vmcnt(31) lgkmcnt(0)
	v_pk_mul_f32 v[168:169], v[148:149], v[152:153]
	v_pk_mul_f32 v[170:171], v[146:147], v[150:151]
	s_waitcnt vmcnt(29)
	v_pk_mul_f32 v[172:173], v[144:145], v[152:153]
	v_pk_mov_b32 v[176:177], v[170:171], v[168:169] op_sel:[1,0]
	v_mov_b32_e32 v171, v169
	v_pk_add_f32 v[168:169], v[176:177], v[170:171]
	v_pk_mul_f32 v[174:175], v[142:143], v[150:151]
	v_add_f32_e32 v2, v168, v169
	v_pk_mov_b32 v[170:171], v[174:175], v[172:173] op_sel:[1,0]
	v_mov_b32_e32 v175, v173
	v_add_f32_dpp v2, v2, v2 quad_perm:[1,0,3,2] row_mask:0xf bank_mask:0xf bound_ctrl:1
	v_pk_add_f32 v[170:171], v[170:171], v[174:175]
	s_waitcnt vmcnt(27)
	v_pk_mul_f32 v[172:173], v[138:139], v[150:151]
	v_add_f32_dpp v2, v2, v2 quad_perm:[2,3,0,1] row_mask:0xf bank_mask:0xf bound_ctrl:1
	s_mov_b32 s9, s8
	s_lshl_b32 s48, s71, 1
	v_add_f32_dpp v2, v2, v2 row_half_mirror row_mask:0xf bank_mask:0xf bound_ctrl:1
	s_add_i32 s80, s2, s6
	s_and_b64 s[2:3], s[6:7], s[8:9]
	v_add_f32_dpp v2, v2, v2 row_ror:8 row_mask:0xf bank_mask:0xf bound_ctrl:1
	v_add_f32_e32 v2, s52, v2
	v_exp_f32_e32 v168, v2
	v_add_f32_e32 v2, v170, v171
	v_pk_mul_f32 v[170:171], v[140:141], v[152:153]
	s_cmp_eq_u32 s3, 0
	v_add_f32_dpp v2, v2, v2 quad_perm:[1,0,3,2] row_mask:0xf bank_mask:0xf bound_ctrl:1
	v_pk_mov_b32 v[174:175], v[172:173], v[170:171] op_sel:[1,0]
	v_mov_b32_e32 v173, v171
	v_add_f32_dpp v2, v2, v2 quad_perm:[2,3,0,1] row_mask:0xf bank_mask:0xf bound_ctrl:1
	v_pk_add_f32 v[170:171], v[174:175], v[172:173]
	s_waitcnt vmcnt(25)
	v_pk_mul_f32 v[172:173], v[136:137], v[152:153]
	v_add_f32_dpp v2, v2, v2 row_half_mirror row_mask:0xf bank_mask:0xf bound_ctrl:1
	v_pk_mul_f32 v[174:175], v[134:135], v[150:151]
	s_cselect_b64 s[76:77], -1, 0
	v_add_f32_dpp v2, v2, v2 row_ror:8 row_mask:0xf bank_mask:0xf bound_ctrl:1
	v_add_f32_e32 v2, s52, v2
	v_exp_f32_e32 v169, v2
	v_add_f32_e32 v2, v170, v171
	v_pk_mov_b32 v[176:177], v[174:175], v[172:173] op_sel:[1,0]
	v_mov_b32_e32 v175, v173
	v_add_f32_dpp v2, v2, v2 quad_perm:[1,0,3,2] row_mask:0xf bank_mask:0xf bound_ctrl:1
	v_pk_add_f32 v[172:173], v[176:177], v[174:175]
	s_waitcnt vmcnt(23)
; #define LAS __attribute__((address_space(3)))
; __device__ __forceinline__ float row16_sum(float v) { v += dppf<0xB1>(v); v += dppf<0x4E>(v); v += dppf<0x141>(v); v += dppf<0x128>(v); return v; }
; __device__ __forceinline__ float dot4(f32x4 a, f32x4 b) { return (a.x * b.x + a.y * b.y) + (a.z * b.z + a.w * b.w); }
; __device__ __forceinline__ float wgt(int delta, int qpos) {
;     const int w = (delta <= 128 ? 1 : 0) + ((((delta & 3) == 0) && delta <= 512) ? 1 : 0) + ((((delta & 15) == 0) && delta <= 2048) ? 1 : 0);
;     return ((unsigned)delta <= (unsigned)qpos) ? (float)w : 0.f;
; }
; __device__ __forceinline__ void c_row_t(const f32x4 k, const f32x4 v, int delta, const f32x4 qa, float negb, f32x4& a, float& l) {
;     const float w = wgt(delta, 1 << 30);
;     const float d = row16_sum(dot4(k, qa));
;     const float p = w * __builtin_amdgcn_exp2f(d + negb);
;     l += p; a += v * p;
; }
; __device__ __forceinline__ void c_issue(CBuf& B, const float* kbase, const float* vbase, long rstride, int off) {
; #pragma unroll
;     for (int q = 0; q < 8; ++q) { B.k[q] = __builtin_nontemporal_load((const f32x4*)(kbase + (long)q * rstride + off)); B.v[q] = __builtin_nontemporal_load((const f32x4*)(vbase + (long)q * rstride + off)); }
; }
; __device__ __forceinline__ void c_consume(const CBuf& B, int delta0, int dstep, int tsel, const LAS float* qs, int off, float negb, CState& S) {
; #pragma unroll
;     for (int t = 0; t < 4; ++t) { if (tsel < 0 || tsel == t) {
;         const f32x4 qa = *(const LAS f32x4*)(qs + t * 512 + off);
; #pragma unroll
;         for (int q = 0; q < 8; ++q) c_row_t(B.k[q], B.v[q], delta0 + q * dstep + t, qa, negb, S.a[t], S.l[t]); } }
; }
	v_pk_mul_f32 v[174:175], v[130:131], v[150:151]
	v_add_f32_dpp v2, v2, v2 quad_perm:[2,3,0,1] row_mask:0xf bank_mask:0xf bound_ctrl:1
	s_cmp_eq_u32 s2, 0
	s_cselect_b64 s[92:93], -1, 0
	v_add_f32_dpp v2, v2, v2 row_half_mirror row_mask:0xf bank_mask:0xf bound_ctrl:1
	s_add_i32 s7, s6, s71
	s_cmpk_lt_i32 s7, 0x81
	v_add_f32_dpp v2, v2, v2 row_ror:8 row_mask:0xf bank_mask:0xf bound_ctrl:1
	v_add_f32_e32 v2, s52, v2
	v_exp_f32_e32 v170, v2
	v_add_f32_e32 v2, v172, v173
	v_pk_mul_f32 v[172:173], v[132:133], v[152:153]
	s_cselect_b64 s[2:3], -1, 0
	v_add_f32_dpp v2, v2, v2 quad_perm:[1,0,3,2] row_mask:0xf bank_mask:0xf bound_ctrl:1
	v_pk_mov_b32 v[176:177], v[174:175], v[172:173] op_sel:[1,0]
	v_mov_b32_e32 v175, v173
	v_add_f32_dpp v2, v2, v2 quad_perm:[2,3,0,1] row_mask:0xf bank_mask:0xf bound_ctrl:1
	v_pk_add_f32 v[172:173], v[176:177], v[174:175]
	s_cmpk_lt_i32 s6, 0x81
	v_add_f32_dpp v2, v2, v2 row_half_mirror row_mask:0xf bank_mask:0xf bound_ctrl:1
	s_cselect_b64 s[36:37], -1, 0
	s_and_b32 s38, s7, 3
	v_add_f32_dpp v2, v2, v2 row_ror:8 row_mask:0xf bank_mask:0xf bound_ctrl:1
	v_add_f32_e32 v2, s52, v2
	v_exp_f32_e32 v171, v2
	v_add_f32_e32 v2, v172, v173
	s_cmp_eq_u32 s38, 0
	s_waitcnt vmcnt(21)
	v_pk_mul_f32 v[174:175], v[128:129], v[152:153]
	v_add_f32_dpp v2, v2, v2 quad_perm:[1,0,3,2] row_mask:0xf bank_mask:0xf bound_ctrl:1
	v_pk_mul_f32 v[176:177], v[126:127], v[150:151]
	s_cselect_b64 s[38:39], -1, 0
	v_add_f32_dpp v2, v2, v2 quad_perm:[2,3,0,1] row_mask:0xf bank_mask:0xf bound_ctrl:1
	s_cmpk_lt_i32 s7, 0x201
	v_pk_mov_b32 v[178:179], v[176:177], v[174:175] op_sel:[1,0]
	v_add_f32_dpp v2, v2, v2 row_half_mirror row_mask:0xf bank_mask:0xf bound_ctrl:1
	v_mov_b32_e32 v177, v175
	s_cselect_b64 s[44:45], -1, 0
	v_add_f32_dpp v2, v2, v2 row_ror:8 row_mask:0xf bank_mask:0xf bound_ctrl:1
	s_cmpk_lt_i32 s6, 0x201
	v_add_f32_e32 v2, s52, v2
	v_pk_add_f32 v[174:175], v[178:179], v[176:177]
	s_cselect_b64 s[46:47], -1, 0
	s_mov_b32 s43, s42
	v_exp_f32_e32 v172, v2
	v_add_f32_e32 v2, v174, v175
	s_and_b64 s[46:47], s[46:47], s[92:93]
	s_and_b64 s[38:39], s[44:45], s[38:39]
	v_cndmask_b32_e64 v174, 0, 1, s[2:3]
	s_and_b64 s[2:3], s[6:7], s[42:43]
	s_cmp_eq_u32 s3, 0
	v_add_f32_dpp v2, v2, v2 quad_perm:[1,0,3,2] row_mask:0xf bank_mask:0xf bound_ctrl:1
	v_cndmask_b32_e64 v167, 0, 1, s[36:37]
	s_cselect_b64 s[36:37], -1, 0
	s_cmp_eq_u32 s2, 0
	v_add_f32_dpp v2, v2, v2 quad_perm:[2,3,0,1] row_mask:0xf bank_mask:0xf bound_ctrl:1
	s_cselect_b64 s[2:3], -1, 0
	s_cmpk_lt_i32 s7, 0x801
	v_add_f32_dpp v2, v2, v2 row_half_mirror row_mask:0xf bank_mask:0xf bound_ctrl:1
	v_cndmask_b32_e64 v4, 0, 1, s[38:39]
	s_cselect_b64 s[38:39], -1, 0
	s_cmpk_lt_i32 s6, 0x801
	v_add_f32_dpp v2, v2, v2 row_ror:8 row_mask:0xf bank_mask:0xf bound_ctrl:1
	s_cselect_b64 s[44:45], -1, 0
	s_and_b64 vcc, s[38:39], s[36:37]
	v_add_f32_e32 v2, s52, v2
	v_addc_co_u32_e32 v4, vcc, v4, v174, vcc
	v_exp_f32_e32 v173, v2
	v_cndmask_b32_e64 v2, 0, 1, s[46:47]
	s_and_b64 vcc, s[44:45], s[2:3]
	v_addc_co_u32_e32 v2, vcc, v2, v167, vcc
	s_cmp_lt_u32 s84, 0x3fffffff
	s_cselect_b64 vcc, -1, 0
	s_cmp_lt_u32 s7, 0x40000001
	v_cvt_f32_ubyte0_e32 v4, v4
	s_cselect_b64 s[2:3], -1, 0
	v_cndmask_b32_e64 v175, 0, v4, s[2:3]
	s_add_i32 s3, s70, s6
	s_add_i32 s2, s48, s6
	s_cmpk_lt_i32 s3, 0x81
	s_cselect_b64 s[36:37], -1, 0
	s_cmpk_lt_i32 s2, 0x81
	s_cselect_b64 s[38:39], -1, 0
	s_and_b64 s[44:45], s[2:3], s[8:9]
	s_cmp_eq_u32 s44, 0
	v_cvt_f32_ubyte0_e32 v2, v2
	s_cselect_b64 s[46:47], -1, 0
	s_cmp_eq_u32 s45, 0
	v_cndmask_b32_e32 v174, 0, v2, vcc
	s_cselect_b64 s[44:45], -1, 0
	s_cmpk_lt_i32 s2, 0x201
	v_pk_mul_f32 v[168:169], v[174:175], v[168:169]
	s_cselect_b64 s[48:49], -1, 0
	s_cmpk_lt_i32 s3, 0x201
	v_pk_fma_f32 v[10:11], v[118:119], v[168:169], v[10:11] op_sel_hi:[1,0,1]
	v_pk_fma_f32 v[12:13], v[120:121], v[168:169], v[12:13] op_sel_hi:[1,0,1]
	s_cselect_b64 s[50:51], -1, 0
	v_add_f32_e32 v2, v165, v168
	v_pk_fma_f32 v[12:13], v[124:125], v[168:169], v[12:13] op_sel:[0,1,0]
	v_pk_fma_f32 v[10:11], v[122:123], v[168:169], v[10:11] op_sel:[0,1,0]
	s_and_b64 s[46:47], s[48:49], s[46:47]
	s_and_b64 s[44:45], s[50:51], s[44:45]
	v_cndmask_b32_e64 v168, 0, 1, s[36:37]
	s_and_b64 s[36:37], s[2:3], s[42:43]
	s_cmp_eq_u32 s37, 0
	v_cndmask_b32_e64 v167, 0, 1, s[38:39]
	s_cselect_b64 s[38:39], -1, 0
	s_cmp_eq_u32 s36, 0
	s_cselect_b64 s[36:37], -1, 0
	s_cmpk_lt_i32 s3, 0x801
	v_cndmask_b32_e64 v165, 0, 1, s[44:45]
	s_cselect_b64 s[44:45], -1, 0
	s_cmpk_lt_i32 s2, 0x801
	v_cndmask_b32_e64 v4, 0, 1, s[46:47]
	s_cselect_b64 s[46:47], -1, 0
	s_and_b64 vcc, s[44:45], s[38:39]
	v_addc_co_u32_e32 v165, vcc, v165, v168, vcc
	s_and_b64 vcc, s[46:47], s[36:37]
	s_nop 0
	v_addc_co_u32_e32 v4, vcc, v4, v167, vcc
	s_cmp_lt_u32 s2, 0x40000001
	s_cselect_b64 vcc, -1, 0
	s_cmp_lt_u32 s3, 0x40000001
	v_cvt_f32_ubyte0_e32 v165, v165
	s_cselect_b64 s[2:3], -1, 0
	s_cmpk_lt_i32 s81, 0x81
	v_add_f32_e32 v2, v2, v169
	v_cvt_f32_ubyte0_e32 v4, v4
	v_cndmask_b32_e64 v169, 0, v165, s[2:3]
	s_cselect_b64 s[2:3], -1, 0
	s_cmpk_lt_i32 s80, 0x81
	v_cndmask_b32_e32 v168, 0, v4, vcc
	s_cselect_b64 s[36:37], -1, 0
	s_cmpk_lt_i32 s80, 0x201
	v_pk_mul_f32 v[168:169], v[168:169], v[170:171]
	s_cselect_b64 s[38:39], -1, 0
	s_cmpk_lt_i32 s81, 0x201
	v_pk_fma_f32 v[10:11], v[114:115], v[168:169], v[10:11] op_sel_hi:[1,0,1]
	v_pk_fma_f32 v[12:13], v[116:117], v[168:169], v[12:13] op_sel_hi:[1,0,1]
	s_cselect_b64 s[44:45], -1, 0
	s_and_b64 s[38:39], s[38:39], s[92:93]
	v_add_f32_e32 v2, v2, v168
	v_pk_fma_f32 v[12:13], v[112:113], v[168:169], v[12:13] op_sel:[0,1,0]
	v_pk_fma_f32 v[10:11], v[110:111], v[168:169], v[10:11] op_sel:[0,1,0]
	v_cndmask_b32_e64 v4, 0, 1, s[38:39]
	s_and_b64 s[38:39], s[44:45], s[76:77]
	v_cndmask_b32_e64 v168, 0, 1, s[2:3]
	s_and_b64 s[2:3], s[80:81], s[42:43]
	s_cmp_eq_u32 s3, 0
	v_cndmask_b32_e64 v167, 0, 1, s[36:37]
	s_cselect_b64 s[36:37], -1, 0
	s_cmp_eq_u32 s2, 0
	s_cselect_b64 s[2:3], -1, 0
	s_cmpk_lt_i32 s81, 0x801
	v_cndmask_b32_e64 v165, 0, 1, s[38:39]
	s_cselect_b64 s[38:39], -1, 0
	s_cmpk_lt_i32 s80, 0x801
	s_cselect_b64 s[44:45], -1, 0
	s_and_b64 vcc, s[38:39], s[36:37]
	v_addc_co_u32_e32 v165, vcc, v165, v168, vcc
	s_and_b64 vcc, s[44:45], s[2:3]
	s_nop 0
	v_addc_co_u32_e32 v4, vcc, v4, v167, vcc
	s_cmp_lt_u32 s80, 0x40000001
	s_cselect_b64 vcc, -1, 0
	s_cmp_lt_u32 s81, 0x40000001
	v_cvt_f32_ubyte0_e32 v4, v4
	v_cvt_f32_ubyte0_e32 v165, v165
	s_cselect_b64 s[2:3], -1, 0
	v_add_f32_e32 v2, v2, v169
	v_cndmask_b32_e64 v169, 0, v165, s[2:3]
	v_cndmask_b32_e32 v168, 0, v4, vcc
	v_pk_mul_f32 v[168:169], v[168:169], v[172:173]
	s_waitcnt vmcnt(19)
; #define LAS __attribute__((address_space(3)))
; __device__ __forceinline__ float row16_sum(float v) { v += dppf<0xB1>(v); v += dppf<0x4E>(v); v += dppf<0x141>(v); v += dppf<0x128>(v); return v; }
; __device__ __forceinline__ float dot4(f32x4 a, f32x4 b) { return (a.x * b.x + a.y * b.y) + (a.z * b.z + a.w * b.w); }
; __device__ __forceinline__ float wgt(int delta, int qpos) {
;     const int w = (delta <= 128 ? 1 : 0) + ((((delta & 3) == 0) && delta <= 512) ? 1 : 0) + ((((delta & 15) == 0) && delta <= 2048) ? 1 : 0);
;     return ((unsigned)delta <= (unsigned)qpos) ? (float)w : 0.f;
; }
; __device__ __forceinline__ void c_row_t(const f32x4 k, const f32x4 v, int delta, const f32x4 qa, float negb, f32x4& a, float& l) {
;     const float w = wgt(delta, 1 << 30);
;     const float d = row16_sum(dot4(k, qa));
;     const float p = w * __builtin_amdgcn_exp2f(d + negb);
;     l += p; a += v * p;
; }
; __device__ __forceinline__ void c_issue(CBuf& B, const float* kbase, const float* vbase, long rstride, int off) {
; #pragma unroll
;     for (int q = 0; q < 8; ++q) { B.k[q] = __builtin_nontemporal_load((const f32x4*)(kbase + (long)q * rstride + off)); B.v[q] = __builtin_nontemporal_load((const f32x4*)(vbase + (long)q * rstride + off)); }
; }
; __device__ __forceinline__ void c_consume(const CBuf& B, int delta0, int dstep, int tsel, const LAS float* qs, int off, float negb, CState& S) {
; #pragma unroll
;     for (int t = 0; t < 4; ++t) { if (tsel < 0 || tsel == t) {
;         const f32x4 qa = *(const LAS f32x4*)(qs + t * 512 + off);
; #pragma unroll
;         for (int q = 0; q < 8; ++q) c_row_t(B.k[q], B.v[q], delta0 + q * dstep + t, qa, negb, S.a[t], S.l[t]); } }
; }
	v_pk_mul_f32 v[170:171], v[98:99], v[150:151]
	v_add_f32_e32 v2, v2, v168
	v_pk_fma_f32 v[10:11], v[106:107], v[168:169], v[10:11] op_sel_hi:[1,0,1]
	v_pk_fma_f32 v[12:13], v[108:109], v[168:169], v[12:13] op_sel_hi:[1,0,1]
	v_add_f32_e32 v2, v2, v169
	v_pk_fma_f32 v[12:13], v[104:105], v[168:169], v[12:13] op_sel:[0,1,0]
	v_pk_fma_f32 v[10:11], v[102:103], v[168:169], v[10:11] op_sel:[0,1,0]
	v_pk_mul_f32 v[168:169], v[100:101], v[152:153]
	s_add_i32 s3, s40, s6
	v_pk_mov_b32 v[172:173], v[170:171], v[168:169] op_sel:[1,0]
	v_mov_b32_e32 v171, v169
	s_add_i32 s2, s10, s6
	v_pk_add_f32 v[168:169], v[172:173], v[170:171]
	s_cmpk_lt_i32 s3, 0x81
	v_add_f32_e32 v4, v168, v169
	s_cselect_b64 s[6:7], -1, 0
	s_cmpk_lt_i32 s2, 0x81
	v_add_f32_dpp v4, v4, v4 quad_perm:[1,0,3,2] row_mask:0xf bank_mask:0xf bound_ctrl:1
	s_cselect_b64 s[36:37], -1, 0
	s_and_b64 s[38:39], s[2:3], s[8:9]
	v_add_f32_dpp v4, v4, v4 quad_perm:[2,3,0,1] row_mask:0xf bank_mask:0xf bound_ctrl:1
	s_cmp_eq_u32 s38, 0
	s_waitcnt vmcnt(18)
	v_pk_mul_f32 v[152:153], v[96:97], v[152:153]
	v_add_f32_dpp v4, v4, v4 row_half_mirror row_mask:0xf bank_mask:0xf bound_ctrl:1
	v_pk_mul_f32 v[150:151], v[94:95], v[150:151]
	s_cselect_b64 s[44:45], -1, 0
	s_cmp_eq_u32 s39, 0
	v_add_f32_dpp v4, v4, v4 row_ror:8 row_mask:0xf bank_mask:0xf bound_ctrl:1
	v_pk_mov_b32 v[170:171], v[150:151], v[152:153] op_sel:[1,0]
	v_mov_b32_e32 v151, v153
	s_cselect_b64 s[38:39], -1, 0
	s_cmpk_lt_i32 s2, 0x201
	v_add_f32_e32 v4, s52, v4
	v_pk_add_f32 v[150:151], v[170:171], v[150:151]
	s_cselect_b64 s[46:47], -1, 0
	s_cmpk_lt_i32 s3, 0x201
	v_exp_f32_e32 v168, v4
	v_add_f32_e32 v4, v150, v151
	s_cselect_b64 s[48:49], -1, 0
	s_and_b64 s[44:45], s[46:47], s[44:45]
	v_add_f32_dpp v4, v4, v4 quad_perm:[1,0,3,2] row_mask:0xf bank_mask:0xf bound_ctrl:1
	s_and_b64 s[38:39], s[48:49], s[38:39]
	v_cndmask_b32_e64 v152, 0, 1, s[6:7]
	s_and_b64 s[6:7], s[2:3], s[42:43]
	v_add_f32_dpp v4, v4, v4 quad_perm:[2,3,0,1] row_mask:0xf bank_mask:0xf bound_ctrl:1
	s_cmp_eq_u32 s7, 0
	v_cndmask_b32_e64 v151, 0, 1, s[36:37]
	v_add_f32_dpp v4, v4, v4 row_half_mirror row_mask:0xf bank_mask:0xf bound_ctrl:1
	s_cselect_b64 s[36:37], -1, 0
	s_cmp_eq_u32 s6, 0
	v_add_f32_dpp v4, v4, v4 row_ror:8 row_mask:0xf bank_mask:0xf bound_ctrl:1
	s_cselect_b64 s[6:7], -1, 0
	s_cmpk_lt_i32 s3, 0x801
	v_add_f32_e32 v4, s52, v4
	v_cndmask_b32_e64 v150, 0, 1, s[38:39]
	s_cselect_b64 s[38:39], -1, 0
	s_cmpk_lt_i32 s2, 0x801
	v_exp_f32_e32 v169, v4
	v_cndmask_b32_e64 v4, 0, 1, s[44:45]
	s_cselect_b64 s[44:45], -1, 0
	s_and_b64 vcc, s[38:39], s[36:37]
	v_addc_co_u32_e32 v150, vcc, v150, v152, vcc
	s_and_b64 vcc, s[44:45], s[6:7]
	s_nop 0
	v_addc_co_u32_e32 v4, vcc, v4, v151, vcc
	s_cmp_lt_u32 s2, 0x40000001
	s_cselect_b64 vcc, -1, 0
	s_cmp_lt_u32 s3, 0x40000001
	v_cvt_f32_ubyte0_e32 v4, v4
	v_cvt_f32_ubyte0_e32 v150, v150
	s_cselect_b64 s[2:3], -1, 0
	v_cndmask_b32_e64 v151, 0, v150, s[2:3]
	v_cndmask_b32_e32 v150, 0, v4, vcc
	v_pk_mul_f32 v[150:151], v[150:151], v[168:169]
	s_nop 0
	v_add_f32_e32 v2, v2, v150
	s_waitcnt vmcnt(17)
	v_pk_fma_f32 v[10:11], v[82:83], v[150:151], v[10:11] op_sel_hi:[1,0,1]
	v_pk_fma_f32 v[12:13], v[84:85], v[150:151], v[12:13] op_sel_hi:[1,0,1]
	v_add_f32_e32 v165, v2, v151
	s_waitcnt vmcnt(16)
	v_pk_fma_f32 v[12:13], v[80:81], v[150:151], v[12:13] op_sel:[0,1,0]
	v_pk_fma_f32 v[10:11], v[78:79], v[150:151], v[10:11] op_sel:[0,1,0]
.LBB0_786:
	s_cmp_lg_u32 s72, 3
	s_cselect_b64 s[2:3], -1, 0
	s_and_b64 s[2:3], s[4:5], s[2:3]
	s_and_b64 vcc, exec, s[2:3]
	s_cbranch_vccnz .LBB0_788
	ds_read_b128 v[150:153], v164 offset:6144
	s_add_i32 s4, s84, 3
	s_add_i32 s7, s74, s4
	s_lshl_b32 s2, s71, 2
	s_mov_b32 s5, s7
	s_waitcnt vmcnt(31) lgkmcnt(0)
	v_pk_mul_f32 v[148:149], v[148:149], v[152:153]
	v_pk_mul_f32 v[146:147], v[146:147], v[150:151]
	s_waitcnt vmcnt(29)
	v_pk_mul_f32 v[144:145], v[144:145], v[152:153]
	v_pk_mov_b32 v[168:169], v[146:147], v[148:149] op_sel:[1,0]
	v_mov_b32_e32 v147, v149
	v_pk_add_f32 v[146:147], v[168:169], v[146:147]
	v_pk_mul_f32 v[142:143], v[142:143], v[150:151]
	v_add_f32_e32 v2, v146, v147
	v_pk_mov_b32 v[148:149], v[142:143], v[144:145] op_sel:[1,0]
	v_mov_b32_e32 v143, v145
	v_add_f32_dpp v2, v2, v2 quad_perm:[1,0,3,2] row_mask:0xf bank_mask:0xf bound_ctrl:1
	v_pk_add_f32 v[142:143], v[148:149], v[142:143]
	s_waitcnt vmcnt(27)
	v_pk_mul_f32 v[140:141], v[140:141], v[152:153]
	v_add_f32_dpp v2, v2, v2 quad_perm:[2,3,0,1] row_mask:0xf bank_mask:0xf bound_ctrl:1
	v_pk_mul_f32 v[138:139], v[138:139], v[150:151]
	s_waitcnt vmcnt(25)
	v_pk_mul_f32 v[136:137], v[136:137], v[152:153]
	v_add_f32_dpp v2, v2, v2 row_half_mirror row_mask:0xf bank_mask:0xf bound_ctrl:1
	v_pk_mul_f32 v[134:135], v[134:135], v[150:151]
	s_mov_b32 s9, s8
	v_add_f32_dpp v2, v2, v2 row_ror:8 row_mask:0xf bank_mask:0xf bound_ctrl:1
	v_add_f32_e32 v2, s52, v2
	v_exp_f32_e32 v146, v2
	v_add_f32_e32 v2, v142, v143
	v_pk_mov_b32 v[142:143], v[138:139], v[140:141] op_sel:[1,0]
	v_mov_b32_e32 v139, v141
	v_add_f32_dpp v2, v2, v2 quad_perm:[1,0,3,2] row_mask:0xf bank_mask:0xf bound_ctrl:1
	v_pk_add_f32 v[138:139], v[142:143], v[138:139]
	v_pk_mov_b32 v[140:141], v[134:135], v[136:137] op_sel:[1,0]
	v_add_f32_dpp v2, v2, v2 quad_perm:[2,3,0,1] row_mask:0xf bank_mask:0xf bound_ctrl:1
	v_mov_b32_e32 v135, v137
	v_pk_add_f32 v[134:135], v[140:141], v[134:135]
	v_add_f32_dpp v2, v2, v2 row_half_mirror row_mask:0xf bank_mask:0xf bound_ctrl:1
	s_lshl_b32 s48, s71, 1
	s_add_i32 s6, s2, s4
	v_add_f32_dpp v2, v2, v2 row_ror:8 row_mask:0xf bank_mask:0xf bound_ctrl:1
	v_add_f32_e32 v2, s52, v2
	v_exp_f32_e32 v147, v2
	v_add_f32_e32 v2, v138, v139
	s_and_b64 s[2:3], s[4:5], s[8:9]
	s_cmp_eq_u32 s3, 0
	v_add_f32_dpp v2, v2, v2 quad_perm:[1,0,3,2] row_mask:0xf bank_mask:0xf bound_ctrl:1
	s_waitcnt vmcnt(23)
; #define LAS __attribute__((address_space(3)))
; __device__ __forceinline__ float row16_sum(float v) { v += dppf<0xB1>(v); v += dppf<0x4E>(v); v += dppf<0x141>(v); v += dppf<0x128>(v); return v; }
; __device__ __forceinline__ float dot4(f32x4 a, f32x4 b) { return (a.x * b.x + a.y * b.y) + (a.z * b.z + a.w * b.w); }
; __device__ __forceinline__ float wgt(int delta, int qpos) {
;     const int w = (delta <= 128 ? 1 : 0) + ((((delta & 3) == 0) && delta <= 512) ? 1 : 0) + ((((delta & 15) == 0) && delta <= 2048) ? 1 : 0);
;     return ((unsigned)delta <= (unsigned)qpos) ? (float)w : 0.f;
; }
; __device__ __forceinline__ void c_row_t(const f32x4 k, const f32x4 v, int delta, const f32x4 qa, float negb, f32x4& a, float& l) {
;     const float w = wgt(delta, 1 << 30);
;     const float d = row16_sum(dot4(k, qa));
;     const float p = w * __builtin_amdgcn_exp2f(d + negb);
;     l += p; a += v * p;
; }
; __device__ __forceinline__ void c_issue(CBuf& B, const float* kbase, const float* vbase, long rstride, int off) {
; #pragma unroll
;     for (int q = 0; q < 8; ++q) { B.k[q] = __builtin_nontemporal_load((const f32x4*)(kbase + (long)q * rstride + off)); B.v[q] = __builtin_nontemporal_load((const f32x4*)(vbase + (long)q * rstride + off)); }
; }
; __device__ __forceinline__ void c_consume(const CBuf& B, int delta0, int dstep, int tsel, const LAS float* qs, int off, float negb, CState& S) {
; #pragma unroll
;     for (int t = 0; t < 4; ++t) { if (tsel < 0 || tsel == t) {
;         const f32x4 qa = *(const LAS f32x4*)(qs + t * 512 + off);
; #pragma unroll
;         for (int q = 0; q < 8; ++q) c_row_t(B.k[q], B.v[q], delta0 + q * dstep + t, qa, negb, S.a[t], S.l[t]); } }
; }
	v_pk_mul_f32 v[132:133], v[132:133], v[152:153]
	v_pk_mul_f32 v[130:131], v[130:131], v[150:151]
	v_add_f32_dpp v2, v2, v2 quad_perm:[2,3,0,1] row_mask:0xf bank_mask:0xf bound_ctrl:1
	s_cselect_b64 s[76:77], -1, 0
	s_cmp_eq_u32 s2, 0
	v_add_f32_dpp v2, v2, v2 row_half_mirror row_mask:0xf bank_mask:0xf bound_ctrl:1
	s_cselect_b64 s[80:81], -1, 0
	s_add_i32 s5, s4, s71
	v_add_f32_dpp v2, v2, v2 row_ror:8 row_mask:0xf bank_mask:0xf bound_ctrl:1
	v_add_f32_e32 v2, s52, v2
	v_exp_f32_e32 v138, v2
	v_add_f32_e32 v2, v134, v135
	v_pk_mov_b32 v[134:135], v[130:131], v[132:133] op_sel:[1,0]
	v_mov_b32_e32 v131, v133
	v_add_f32_dpp v2, v2, v2 quad_perm:[1,0,3,2] row_mask:0xf bank_mask:0xf bound_ctrl:1
	v_pk_add_f32 v[130:131], v[134:135], v[130:131]
	s_cmpk_lt_i32 s5, 0x81
	v_add_f32_dpp v2, v2, v2 quad_perm:[2,3,0,1] row_mask:0xf bank_mask:0xf bound_ctrl:1
	s_cselect_b64 s[2:3], -1, 0
	s_cmpk_lt_i32 s4, 0x81
	v_add_f32_dpp v2, v2, v2 row_half_mirror row_mask:0xf bank_mask:0xf bound_ctrl:1
	s_cselect_b64 s[36:37], -1, 0
	s_and_b32 s38, s5, 3
	v_add_f32_dpp v2, v2, v2 row_ror:8 row_mask:0xf bank_mask:0xf bound_ctrl:1
	v_add_f32_e32 v2, s52, v2
	v_exp_f32_e32 v139, v2
	v_add_f32_e32 v2, v130, v131
	s_cmp_eq_u32 s38, 0
	s_waitcnt vmcnt(21)
	v_pk_mul_f32 v[128:129], v[128:129], v[152:153]
	v_add_f32_dpp v2, v2, v2 quad_perm:[1,0,3,2] row_mask:0xf bank_mask:0xf bound_ctrl:1
	v_pk_mul_f32 v[126:127], v[126:127], v[150:151]
	s_cselect_b64 s[38:39], -1, 0
	v_add_f32_dpp v2, v2, v2 quad_perm:[2,3,0,1] row_mask:0xf bank_mask:0xf bound_ctrl:1
	s_cmpk_lt_i32 s5, 0x201
	v_pk_mov_b32 v[132:133], v[126:127], v[128:129] op_sel:[1,0]
	v_add_f32_dpp v2, v2, v2 row_half_mirror row_mask:0xf bank_mask:0xf bound_ctrl:1
	v_mov_b32_e32 v127, v129
	s_cselect_b64 s[44:45], -1, 0
	v_add_f32_dpp v2, v2, v2 row_ror:8 row_mask:0xf bank_mask:0xf bound_ctrl:1
	s_cmpk_lt_i32 s4, 0x201
	v_add_f32_e32 v2, s52, v2
	v_pk_add_f32 v[126:127], v[132:133], v[126:127]
	s_cselect_b64 s[46:47], -1, 0
	s_mov_b32 s43, s42
	v_exp_f32_e32 v130, v2
	v_add_f32_e32 v2, v126, v127
	s_and_b64 s[46:47], s[46:47], s[80:81]
	s_and_b64 s[38:39], s[44:45], s[38:39]
	v_cndmask_b32_e64 v127, 0, 1, s[2:3]
	s_and_b64 s[2:3], s[4:5], s[42:43]
	s_cmp_eq_u32 s3, 0
	v_add_f32_dpp v2, v2, v2 quad_perm:[1,0,3,2] row_mask:0xf bank_mask:0xf bound_ctrl:1
	v_cndmask_b32_e64 v126, 0, 1, s[36:37]
	s_cselect_b64 s[36:37], -1, 0
	s_cmp_eq_u32 s2, 0
	v_add_f32_dpp v2, v2, v2 quad_perm:[2,3,0,1] row_mask:0xf bank_mask:0xf bound_ctrl:1
	s_cselect_b64 s[2:3], -1, 0
	s_cmpk_lt_i32 s5, 0x801
	v_add_f32_dpp v2, v2, v2 row_half_mirror row_mask:0xf bank_mask:0xf bound_ctrl:1
	v_cndmask_b32_e64 v4, 0, 1, s[38:39]
	s_cselect_b64 s[38:39], -1, 0
	s_cmpk_lt_i32 s4, 0x801
	v_add_f32_dpp v2, v2, v2 row_ror:8 row_mask:0xf bank_mask:0xf bound_ctrl:1
	s_cselect_b64 s[44:45], -1, 0
	s_and_b64 vcc, s[38:39], s[36:37]
	v_add_f32_e32 v2, s52, v2
	v_addc_co_u32_e32 v4, vcc, v4, v127, vcc
	v_exp_f32_e32 v131, v2
	v_cndmask_b32_e64 v2, 0, 1, s[46:47]
	s_and_b64 vcc, s[44:45], s[2:3]
	v_addc_co_u32_e32 v2, vcc, v2, v126, vcc
	s_cmp_lt_u32 s84, 0x3ffffffe
	s_cselect_b64 vcc, -1, 0
	s_cmp_lt_u32 s5, 0x40000001
	v_cvt_f32_ubyte0_e32 v4, v4
	s_cselect_b64 s[2:3], -1, 0
	v_cndmask_b32_e64 v127, 0, v4, s[2:3]
	s_add_i32 s3, s70, s4
	s_add_i32 s2, s48, s4
	s_cmpk_lt_i32 s3, 0x81
	s_cselect_b64 s[36:37], -1, 0
	s_cmpk_lt_i32 s2, 0x81
	s_cselect_b64 s[38:39], -1, 0
	s_and_b64 s[44:45], s[2:3], s[8:9]
	s_cmp_eq_u32 s44, 0
	s_cselect_b64 s[46:47], -1, 0
	s_cmp_eq_u32 s45, 0
	v_cvt_f32_ubyte0_e32 v2, v2
	s_cselect_b64 s[44:45], -1, 0
	s_cmpk_lt_i32 s2, 0x201
	v_cndmask_b32_e32 v126, 0, v2, vcc
	s_cselect_b64 s[48:49], -1, 0
	s_cmpk_lt_i32 s3, 0x201
	v_pk_mul_f32 v[126:127], v[126:127], v[146:147]
	s_cselect_b64 s[50:51], -1, 0
	v_add_f32_e32 v2, v5, v126
	v_pk_fma_f32 v[4:5], v[118:119], v[126:127], v[6:7] op_sel_hi:[1,0,1]
	s_and_b64 s[46:47], s[48:49], s[46:47]
	s_and_b64 s[44:45], s[50:51], s[44:45]
	v_cndmask_b32_e64 v119, 0, 1, s[36:37]
	s_and_b64 s[36:37], s[2:3], s[42:43]
	s_cmp_eq_u32 s37, 0
	v_cndmask_b32_e64 v118, 0, 1, s[38:39]
	s_cselect_b64 s[38:39], -1, 0
	s_cmp_eq_u32 s36, 0
	s_cselect_b64 s[36:37], -1, 0
	s_cmpk_lt_i32 s3, 0x801
	v_pk_fma_f32 v[6:7], v[120:121], v[126:127], v[8:9] op_sel_hi:[1,0,1]
	v_cndmask_b32_e64 v9, 0, 1, s[44:45]
	s_cselect_b64 s[44:45], -1, 0
	s_cmpk_lt_i32 s2, 0x801
	v_cndmask_b32_e64 v8, 0, 1, s[46:47]
	s_cselect_b64 s[46:47], -1, 0
	s_and_b64 vcc, s[44:45], s[38:39]
	v_addc_co_u32_e32 v9, vcc, v9, v119, vcc
	s_and_b64 vcc, s[46:47], s[36:37]
	s_nop 0
	v_addc_co_u32_e32 v8, vcc, v8, v118, vcc
	s_cmp_lt_u32 s2, 0x40000001
	s_cselect_b64 vcc, -1, 0
	s_cmp_lt_u32 s3, 0x40000001
	v_cvt_f32_ubyte0_e32 v9, v9
	s_cselect_b64 s[2:3], -1, 0
	s_cmpk_lt_i32 s7, 0x81
	v_cvt_f32_ubyte0_e32 v8, v8
	v_cndmask_b32_e64 v9, 0, v9, s[2:3]
	s_cselect_b64 s[2:3], -1, 0
	s_cmpk_lt_i32 s6, 0x81
	v_cndmask_b32_e32 v8, 0, v8, vcc
	s_cselect_b64 s[36:37], -1, 0
	s_cmpk_lt_i32 s6, 0x201
	v_pk_fma_f32 v[6:7], v[124:125], v[126:127], v[6:7] op_sel:[0,1,0]
	v_pk_fma_f32 v[4:5], v[122:123], v[126:127], v[4:5] op_sel:[0,1,0]
	v_pk_mul_f32 v[8:9], v[8:9], v[138:139]
	s_cselect_b64 s[38:39], -1, 0
	s_cmpk_lt_i32 s7, 0x201
	v_add_f32_e32 v2, v2, v127
	v_pk_fma_f32 v[4:5], v[114:115], v[8:9], v[4:5] op_sel_hi:[1,0,1]
	v_pk_fma_f32 v[6:7], v[116:117], v[8:9], v[6:7] op_sel_hi:[1,0,1]
	s_cselect_b64 s[44:45], -1, 0
	s_and_b64 s[38:39], s[38:39], s[80:81]
	v_add_f32_e32 v2, v2, v8
	v_pk_fma_f32 v[6:7], v[112:113], v[8:9], v[6:7] op_sel:[0,1,0]
	v_pk_fma_f32 v[4:5], v[110:111], v[8:9], v[4:5] op_sel:[0,1,0]
	v_cndmask_b32_e64 v8, 0, 1, s[38:39]
	s_and_b64 s[38:39], s[44:45], s[76:77]
	v_cndmask_b32_e64 v111, 0, 1, s[2:3]
	s_and_b64 s[2:3], s[6:7], s[42:43]
	s_cmp_eq_u32 s3, 0
	v_cndmask_b32_e64 v110, 0, 1, s[36:37]
	s_cselect_b64 s[36:37], -1, 0
	s_cmp_eq_u32 s2, 0
	s_cselect_b64 s[2:3], -1, 0
	s_cmpk_lt_i32 s7, 0x801
	v_add_f32_e32 v2, v2, v9
	v_cndmask_b32_e64 v9, 0, 1, s[38:39]
	s_cselect_b64 s[38:39], -1, 0
	s_cmpk_lt_i32 s6, 0x801
	s_cselect_b64 s[44:45], -1, 0
	s_and_b64 vcc, s[38:39], s[36:37]
	v_addc_co_u32_e32 v9, vcc, v9, v111, vcc
	s_and_b64 vcc, s[44:45], s[2:3]
	s_nop 0
	v_addc_co_u32_e32 v8, vcc, v8, v110, vcc
	s_cmp_lt_u32 s6, 0x40000001
	s_cselect_b64 vcc, -1, 0
	s_cmp_lt_u32 s7, 0x40000001
	v_cvt_f32_ubyte0_e32 v9, v9
	s_cselect_b64 s[2:3], -1, 0
	v_cndmask_b32_e64 v9, 0, v9, s[2:3]
	s_add_i32 s3, s40, s4
	s_add_i32 s2, s10, s4
	s_cmpk_lt_i32 s3, 0x81
	s_cselect_b64 s[4:5], -1, 0
	s_cmpk_lt_i32 s2, 0x81
	v_cvt_f32_ubyte0_e32 v8, v8
	s_cselect_b64 s[6:7], -1, 0
	s_and_b64 s[36:37], s[2:3], s[8:9]
	v_cndmask_b32_e32 v8, 0, v8, vcc
	s_cmp_eq_u32 s36, 0
	v_pk_mul_f32 v[8:9], v[8:9], v[130:131]
	s_cselect_b64 s[38:39], -1, 0
	s_cmp_eq_u32 s37, 0
	v_add_f32_e32 v2, v2, v8
	v_pk_fma_f32 v[4:5], v[106:107], v[8:9], v[4:5] op_sel_hi:[1,0,1]
	v_pk_fma_f32 v[6:7], v[108:109], v[8:9], v[6:7] op_sel_hi:[1,0,1]
	s_cselect_b64 s[36:37], -1, 0
	s_cmpk_lt_i32 s2, 0x201
	v_add_f32_e32 v2, v2, v9
	s_waitcnt vmcnt(20)
; #define LAS __attribute__((address_space(3)))
; __device__ __forceinline__ float row16_sum(float v) { v += dppf<0xB1>(v); v += dppf<0x4E>(v); v += dppf<0x141>(v); v += dppf<0x128>(v); return v; }
; __device__ __forceinline__ float dot4(f32x4 a, f32x4 b) { return (a.x * b.x + a.y * b.y) + (a.z * b.z + a.w * b.w); }
; __device__ __forceinline__ float wgt(int delta, int qpos) {
;     const int w = (delta <= 128 ? 1 : 0) + ((((delta & 3) == 0) && delta <= 512) ? 1 : 0) + ((((delta & 15) == 0) && delta <= 2048) ? 1 : 0);
;     return ((unsigned)delta <= (unsigned)qpos) ? (float)w : 0.f;
; }
; __device__ __forceinline__ void c_row_t(const f32x4 k, const f32x4 v, int delta, const f32x4 qa, float negb, f32x4& a, float& l) {
;     const float w = wgt(delta, 1 << 30);
;     const float d = row16_sum(dot4(k, qa));
;     const float p = w * __builtin_amdgcn_exp2f(d + negb);
;     l += p; a += v * p;
; }
; __device__ __forceinline__ void c_issue(CBuf& B, const float* kbase, const float* vbase, long rstride, int off) {
; #pragma unroll
;     for (int q = 0; q < 8; ++q) { B.k[q] = __builtin_nontemporal_load((const f32x4*)(kbase + (long)q * rstride + off)); B.v[q] = __builtin_nontemporal_load((const f32x4*)(vbase + (long)q * rstride + off)); }
; }
; __device__ __forceinline__ void c_consume(const CBuf& B, int delta0, int dstep, int tsel, const LAS float* qs, int off, float negb, CState& S) {
; #pragma unroll
;     for (int t = 0; t < 4; ++t) { if (tsel < 0 || tsel == t) {
;         const f32x4 qa = *(const LAS f32x4*)(qs + t * 512 + off);
; #pragma unroll
;         for (int q = 0; q < 8; ++q) c_row_t(B.k[q], B.v[q], delta0 + q * dstep + t, qa, negb, S.a[t], S.l[t]); } }
; }
	v_pk_fma_f32 v[6:7], v[104:105], v[8:9], v[6:7] op_sel:[0,1,0]
	v_pk_fma_f32 v[4:5], v[102:103], v[8:9], v[4:5] op_sel:[0,1,0]
	s_waitcnt vmcnt(19)
	v_pk_mul_f32 v[8:9], v[100:101], v[152:153]
	v_pk_mul_f32 v[98:99], v[98:99], v[150:151]
	s_cselect_b64 s[44:45], -1, 0
	s_cmpk_lt_i32 s3, 0x201
	v_pk_mov_b32 v[100:101], v[98:99], v[8:9] op_sel:[1,0]
	v_mov_b32_e32 v99, v9
	s_waitcnt vmcnt(18)
	v_pk_mul_f32 v[96:97], v[96:97], v[152:153]
	v_pk_mul_f32 v[94:95], v[94:95], v[150:151]
	s_cselect_b64 s[46:47], -1, 0
	v_pk_add_f32 v[8:9], v[100:101], v[98:99]
	v_pk_mov_b32 v[98:99], v[94:95], v[96:97] op_sel:[1,0]
	v_mov_b32_e32 v95, v97
	s_and_b64 s[38:39], s[44:45], s[38:39]
	s_and_b64 s[36:37], s[46:47], s[36:37]
	v_cndmask_b32_e64 v97, 0, 1, s[4:5]
	s_and_b64 s[4:5], s[2:3], s[42:43]
	v_pk_add_f32 v[94:95], v[98:99], v[94:95]
	s_cmp_eq_u32 s5, 0
	v_add_f32_e32 v8, v8, v9
	v_add_f32_e32 v9, v94, v95
	v_cndmask_b32_e64 v96, 0, 1, s[6:7]
	s_cselect_b64 s[6:7], -1, 0
	s_cmp_eq_u32 s4, 0
	v_add_f32_dpp v8, v8, v8 quad_perm:[1,0,3,2] row_mask:0xf bank_mask:0xf bound_ctrl:1
	v_add_f32_dpp v9, v9, v9 quad_perm:[1,0,3,2] row_mask:0xf bank_mask:0xf bound_ctrl:1
	s_cselect_b64 s[4:5], -1, 0
	s_cmpk_lt_i32 s3, 0x801
	v_add_f32_dpp v8, v8, v8 quad_perm:[2,3,0,1] row_mask:0xf bank_mask:0xf bound_ctrl:1
	v_add_f32_dpp v9, v9, v9 quad_perm:[2,3,0,1] row_mask:0xf bank_mask:0xf bound_ctrl:1
	v_cndmask_b32_e64 v95, 0, 1, s[36:37]
	s_cselect_b64 s[36:37], -1, 0
	s_cmpk_lt_i32 s2, 0x801
	v_add_f32_dpp v8, v8, v8 row_half_mirror row_mask:0xf bank_mask:0xf bound_ctrl:1
	v_add_f32_dpp v9, v9, v9 row_half_mirror row_mask:0xf bank_mask:0xf bound_ctrl:1
	v_cndmask_b32_e64 v94, 0, 1, s[38:39]
	s_cselect_b64 s[38:39], -1, 0
	s_and_b64 vcc, s[36:37], s[6:7]
	v_add_f32_dpp v8, v8, v8 row_ror:8 row_mask:0xf bank_mask:0xf bound_ctrl:1
	v_add_f32_dpp v9, v9, v9 row_ror:8 row_mask:0xf bank_mask:0xf bound_ctrl:1
	v_addc_co_u32_e32 v95, vcc, v95, v97, vcc
	v_add_f32_e32 v8, s52, v8
	v_add_f32_e32 v9, s52, v9
	s_and_b64 vcc, s[38:39], s[4:5]
	v_exp_f32_e32 v8, v8
	v_exp_f32_e32 v9, v9
	v_addc_co_u32_e32 v94, vcc, v94, v96, vcc
	s_cmp_lt_u32 s2, 0x40000001
	s_cselect_b64 vcc, -1, 0
	s_cmp_lt_u32 s3, 0x40000001
	v_cvt_f32_ubyte0_e32 v94, v94
	v_cvt_f32_ubyte0_e32 v95, v95
	s_cselect_b64 s[2:3], -1, 0
	v_cndmask_b32_e64 v95, 0, v95, s[2:3]
	v_cndmask_b32_e32 v94, 0, v94, vcc
	v_pk_mul_f32 v[94:95], v[94:95], v[8:9]
	s_nop 0
	v_add_f32_e32 v2, v2, v94
	s_waitcnt vmcnt(17)
	v_pk_fma_f32 v[82:83], v[82:83], v[94:95], v[4:5] op_sel_hi:[1,0,1]
	v_pk_fma_f32 v[6:7], v[84:85], v[94:95], v[6:7] op_sel_hi:[1,0,1]
	v_add_f32_e32 v5, v2, v95
	s_waitcnt vmcnt(16)
	v_pk_fma_f32 v[8:9], v[80:81], v[94:95], v[6:7] op_sel:[0,1,0]
	v_pk_fma_f32 v[6:7], v[78:79], v[94:95], v[82:83] op_sel:[0,1,0]
